# DN scan: the dead operand prefetch of the last step of each chunk removed (chunk barrier no longer waits for it); includes P6 staging de-serialisation
# speedup vs baseline: 1.0106x; 1.0106x over previous
.LBB0_906:
	v_readfirstlane_b32 s100, v92
	v_readfirstlane_b32 s101, v93
	s_sub_u32 s100, s100, m0
	s_subb_u32 s101, s101, 0
	s_waitcnt lgkmcnt(0)
	v_pk_mul_f32 v[114:115], v[34:35], v[74:75] op_sel_hi:[0,1]
	v_pk_mul_f32 v[116:117], v[34:35], v[78:79] op_sel_hi:[0,1]
	v_pk_fma_f32 v[106:107], v[114:115], v[2:3], 0 op_sel_hi:[1,1,0]
	v_pk_fma_f32 v[108:109], v[114:115], v[30:31], 0 op_sel_hi:[1,1,0]
	v_pk_mul_f32 v[118:119], v[34:35], v[80:81] op_sel_hi:[0,1]
	ds_read_b128 v[66:69], v94 offset:800
	v_pk_fma_f32 v[106:107], v[116:117], v[4:5], v[106:107]
	v_pk_fma_f32 v[108:109], v[116:117], v[32:33], v[108:109]
	v_pk_mul_f32 v[120:121], v[34:35], v[82:83] op_sel_hi:[0,1]
	ds_read_b128 v[62:65], v94 offset:816
	v_pk_fma_f32 v[106:107], v[118:119], v[6:7], v[106:107]
	v_pk_fma_f32 v[108:109], v[118:119], v[26:27], v[108:109]
	v_pk_mul_f32 v[122:123], v[34:35], v[84:85] op_sel_hi:[0,1]
	ds_read_b128 v[58:61], v94 offset:832
	v_pk_fma_f32 v[106:107], v[120:121], v[8:9], v[106:107]
	v_pk_fma_f32 v[108:109], v[120:121], v[28:29], v[108:109]
	v_pk_mul_f32 v[124:125], v[34:35], v[86:87] op_sel_hi:[0,1]
	ds_read_b128 v[54:57], v94 offset:848
	v_pk_fma_f32 v[106:107], v[122:123], v[14:15], v[106:107]
	v_pk_fma_f32 v[108:109], v[122:123], v[22:23], v[108:109]
	v_pk_mul_f32 v[126:127], v[34:35], v[88:89] op_sel_hi:[0,1]
	ds_read_b128 v[50:53], v94 offset:1056
	v_pk_fma_f32 v[106:107], v[124:125], v[16:17], v[106:107]
	v_pk_fma_f32 v[108:109], v[124:125], v[24:25], v[108:109]
	v_pk_mul_f32 v[128:129], v[34:35], v[90:91] op_sel_hi:[0,1]
	ds_read_b128 v[46:49], v94 offset:1072
	v_pk_fma_f32 v[106:107], v[126:127], v[10:11], v[106:107]
	v_pk_fma_f32 v[108:109], v[126:127], v[18:19], v[108:109]
	ds_read_b128 v[42:45], v94 offset:1088
	v_pk_fma_f32 v[106:107], v[128:129], v[12:13], v[106:107]
	v_pk_fma_f32 v[108:109], v[128:129], v[20:21], v[108:109]
	ds_read_b128 v[38:41], v94 offset:1104
	v_add_f32_e32 v130, v106, v107
	v_add_f32_e32 v131, v108, v109
	ds_read_b32 v0, v95 offset:1312
	v_add_f32_dpp v130, v130, v130 quad_perm:[1,0,3,2] row_mask:0xf bank_mask:0xf bound_ctrl:1
	v_add_f32_dpp v131, v131, v131 quad_perm:[1,0,3,2] row_mask:0xf bank_mask:0xf bound_ctrl:1
	ds_read_b96 v[70:72], v1 offset:1568
	v_add_f32_dpp v130, v130, v130 quad_perm:[2,3,0,1] row_mask:0xf bank_mask:0xf bound_ctrl:1
	v_add_f32_dpp v131, v131, v131 quad_perm:[2,3,0,1] row_mask:0xf bank_mask:0xf bound_ctrl:1
	v_sub_f32_e32 v130, v73, v130
	v_mul_f32_e32 v130, v35, v130
	v_fma_f32 v131, v36, v130, v131
	v_cvt_pk_bf16_f32 v132, v131, v131
	v_pk_fma_f32 v[74:75], v[2:3], v[130:131], v[114:115] op_sel_hi:[1,0,1]
	v_pk_fma_f32 v[78:79], v[4:5], v[130:131], v[116:117] op_sel_hi:[1,0,1]
	global_store_short v144, v132, s[100:101]
	v_pk_fma_f32 v[80:81], v[6:7], v[130:131], v[118:119] op_sel_hi:[1,0,1]
	v_pk_fma_f32 v[82:83], v[8:9], v[130:131], v[120:121] op_sel_hi:[1,0,1]
	v_pk_fma_f32 v[84:85], v[14:15], v[130:131], v[122:123] op_sel_hi:[1,0,1]
	v_pk_fma_f32 v[86:87], v[16:17], v[130:131], v[124:125] op_sel_hi:[1,0,1]
	v_pk_fma_f32 v[88:89], v[10:11], v[130:131], v[126:127] op_sel_hi:[1,0,1]
	v_pk_fma_f32 v[90:91], v[12:13], v[130:131], v[128:129] op_sel_hi:[1,0,1]
	s_waitcnt lgkmcnt(0)
	v_pk_mul_f32 v[114:115], v[70:71], v[74:75] op_sel_hi:[0,1]
	v_pk_mul_f32 v[116:117], v[70:71], v[78:79] op_sel_hi:[0,1]
	v_pk_fma_f32 v[110:111], v[114:115], v[50:51], 0 op_sel_hi:[1,1,0]
	v_pk_fma_f32 v[112:113], v[114:115], v[66:67], 0 op_sel_hi:[1,1,0]
	v_pk_mul_f32 v[118:119], v[70:71], v[80:81] op_sel_hi:[0,1]
	ds_read_b128 v[30:33], v94 offset:1600
	v_pk_fma_f32 v[110:111], v[116:117], v[52:53], v[110:111]
	v_pk_fma_f32 v[112:113], v[116:117], v[68:69], v[112:113]
	v_pk_mul_f32 v[120:121], v[70:71], v[82:83] op_sel_hi:[0,1]
	ds_read_b128 v[26:29], v94 offset:1616
	v_pk_fma_f32 v[110:111], v[118:119], v[46:47], v[110:111]
	v_pk_fma_f32 v[112:113], v[118:119], v[62:63], v[112:113]
	v_pk_mul_f32 v[122:123], v[70:71], v[84:85] op_sel_hi:[0,1]
	ds_read_b128 v[22:25], v94 offset:1632
	v_pk_fma_f32 v[110:111], v[120:121], v[48:49], v[110:111]
	v_pk_fma_f32 v[112:113], v[120:121], v[64:65], v[112:113]
	v_pk_mul_f32 v[124:125], v[70:71], v[86:87] op_sel_hi:[0,1]
	ds_read_b128 v[18:21], v94 offset:1648
	v_pk_fma_f32 v[110:111], v[122:123], v[42:43], v[110:111]
	v_pk_fma_f32 v[112:113], v[122:123], v[58:59], v[112:113]
	v_pk_mul_f32 v[126:127], v[70:71], v[88:89] op_sel_hi:[0,1]
	ds_read_b128 v[2:5], v94 offset:1856
	v_pk_fma_f32 v[110:111], v[124:125], v[44:45], v[110:111]
	v_pk_fma_f32 v[112:113], v[124:125], v[60:61], v[112:113]
	v_pk_mul_f32 v[128:129], v[70:71], v[90:91] op_sel_hi:[0,1]
	ds_read_b128 v[6:9], v94 offset:1872
	v_pk_fma_f32 v[110:111], v[126:127], v[38:39], v[110:111]
	v_pk_fma_f32 v[112:113], v[126:127], v[54:55], v[112:113]
	ds_read_b128 v[14:17], v94 offset:1888
	v_pk_fma_f32 v[110:111], v[128:129], v[40:41], v[110:111]
	v_pk_fma_f32 v[112:113], v[128:129], v[56:57], v[112:113]
	ds_read_b128 v[10:13], v94 offset:1904
	v_add_f32_e32 v134, v110, v111
	v_add_f32_e32 v135, v112, v113
	ds_read_b32 v73, v95 offset:2112
	v_add_f32_dpp v134, v134, v134 quad_perm:[1,0,3,2] row_mask:0xf bank_mask:0xf bound_ctrl:1
	v_add_f32_dpp v135, v135, v135 quad_perm:[1,0,3,2] row_mask:0xf bank_mask:0xf bound_ctrl:1
	ds_read_b96 v[34:36], v1 offset:2368
	v_add_f32_dpp v134, v134, v134 quad_perm:[2,3,0,1] row_mask:0xf bank_mask:0xf bound_ctrl:1
	v_add_f32_dpp v135, v135, v135 quad_perm:[2,3,0,1] row_mask:0xf bank_mask:0xf bound_ctrl:1
	v_sub_f32_e32 v134, v0, v134
	v_mul_f32_e32 v134, v71, v134
	v_fma_f32 v135, v72, v134, v135
	v_cvt_pk_bf16_f32 v133, v135, v135
	v_pk_fma_f32 v[74:75], v[50:51], v[134:135], v[114:115] op_sel_hi:[1,0,1]
	v_pk_fma_f32 v[78:79], v[52:53], v[134:135], v[116:117] op_sel_hi:[1,0,1]
	global_store_short v145, v133, s[100:101]
	v_pk_fma_f32 v[80:81], v[46:47], v[134:135], v[118:119] op_sel_hi:[1,0,1]
	v_pk_fma_f32 v[82:83], v[48:49], v[134:135], v[120:121] op_sel_hi:[1,0,1]
	v_pk_fma_f32 v[84:85], v[42:43], v[134:135], v[122:123] op_sel_hi:[1,0,1]
	v_pk_fma_f32 v[86:87], v[44:45], v[134:135], v[124:125] op_sel_hi:[1,0,1]
	v_pk_fma_f32 v[88:89], v[38:39], v[134:135], v[126:127] op_sel_hi:[1,0,1]
	v_pk_fma_f32 v[90:91], v[40:41], v[134:135], v[128:129] op_sel_hi:[1,0,1]
	s_waitcnt lgkmcnt(0)
	v_pk_mul_f32 v[114:115], v[34:35], v[74:75] op_sel_hi:[0,1]
	v_pk_mul_f32 v[116:117], v[34:35], v[78:79] op_sel_hi:[0,1]
	v_pk_fma_f32 v[106:107], v[114:115], v[2:3], 0 op_sel_hi:[1,1,0]
	v_pk_fma_f32 v[108:109], v[114:115], v[30:31], 0 op_sel_hi:[1,1,0]
	v_pk_mul_f32 v[118:119], v[34:35], v[80:81] op_sel_hi:[0,1]
	ds_read_b128 v[66:69], v94 offset:2400
	v_pk_fma_f32 v[106:107], v[116:117], v[4:5], v[106:107]
	v_pk_fma_f32 v[108:109], v[116:117], v[32:33], v[108:109]
	v_pk_mul_f32 v[120:121], v[34:35], v[82:83] op_sel_hi:[0,1]
	ds_read_b128 v[62:65], v94 offset:2416
	v_pk_fma_f32 v[106:107], v[118:119], v[6:7], v[106:107]
	v_pk_fma_f32 v[108:109], v[118:119], v[26:27], v[108:109]
	v_pk_mul_f32 v[122:123], v[34:35], v[84:85] op_sel_hi:[0,1]
	ds_read_b128 v[58:61], v94 offset:2432
	v_pk_fma_f32 v[106:107], v[120:121], v[8:9], v[106:107]
	v_pk_fma_f32 v[108:109], v[120:121], v[28:29], v[108:109]
	v_pk_mul_f32 v[124:125], v[34:35], v[86:87] op_sel_hi:[0,1]
	ds_read_b128 v[54:57], v94 offset:2448
	v_pk_fma_f32 v[106:107], v[122:123], v[14:15], v[106:107]
	v_pk_fma_f32 v[108:109], v[122:123], v[22:23], v[108:109]
	v_pk_mul_f32 v[126:127], v[34:35], v[88:89] op_sel_hi:[0,1]
	ds_read_b128 v[50:53], v94 offset:2656
	v_pk_fma_f32 v[106:107], v[124:125], v[16:17], v[106:107]
	v_pk_fma_f32 v[108:109], v[124:125], v[24:25], v[108:109]
	v_pk_mul_f32 v[128:129], v[34:35], v[90:91] op_sel_hi:[0,1]
	ds_read_b128 v[46:49], v94 offset:2672
	v_pk_fma_f32 v[106:107], v[126:127], v[10:11], v[106:107]
	v_pk_fma_f32 v[108:109], v[126:127], v[18:19], v[108:109]
	ds_read_b128 v[42:45], v94 offset:2688
	v_pk_fma_f32 v[106:107], v[128:129], v[12:13], v[106:107]
	v_pk_fma_f32 v[108:109], v[128:129], v[20:21], v[108:109]
	ds_read_b128 v[38:41], v94 offset:2704
	v_add_f32_e32 v130, v106, v107
	v_add_f32_e32 v131, v108, v109
	ds_read_b32 v0, v95 offset:2912
	v_add_f32_dpp v130, v130, v130 quad_perm:[1,0,3,2] row_mask:0xf bank_mask:0xf bound_ctrl:1
	v_add_f32_dpp v131, v131, v131 quad_perm:[1,0,3,2] row_mask:0xf bank_mask:0xf bound_ctrl:1
	ds_read_b96 v[70:72], v1 offset:3168
	v_add_f32_dpp v130, v130, v130 quad_perm:[2,3,0,1] row_mask:0xf bank_mask:0xf bound_ctrl:1
	v_add_f32_dpp v131, v131, v131 quad_perm:[2,3,0,1] row_mask:0xf bank_mask:0xf bound_ctrl:1
	v_sub_f32_e32 v130, v73, v130
	v_mul_f32_e32 v130, v35, v130
	v_fma_f32 v131, v36, v130, v131
	v_cvt_pk_bf16_f32 v132, v131, v131
	v_pk_fma_f32 v[74:75], v[2:3], v[130:131], v[114:115] op_sel_hi:[1,0,1]
	v_pk_fma_f32 v[78:79], v[4:5], v[130:131], v[116:117] op_sel_hi:[1,0,1]
	global_store_short v146, v132, s[100:101]
	v_pk_fma_f32 v[80:81], v[6:7], v[130:131], v[118:119] op_sel_hi:[1,0,1]
	v_pk_fma_f32 v[82:83], v[8:9], v[130:131], v[120:121] op_sel_hi:[1,0,1]
	v_pk_fma_f32 v[84:85], v[14:15], v[130:131], v[122:123] op_sel_hi:[1,0,1]
	v_pk_fma_f32 v[86:87], v[16:17], v[130:131], v[124:125] op_sel_hi:[1,0,1]
	v_pk_fma_f32 v[88:89], v[10:11], v[130:131], v[126:127] op_sel_hi:[1,0,1]
	v_pk_fma_f32 v[90:91], v[12:13], v[130:131], v[128:129] op_sel_hi:[1,0,1]
	s_waitcnt lgkmcnt(0)
	v_pk_mul_f32 v[114:115], v[70:71], v[74:75] op_sel_hi:[0,1]
	v_pk_mul_f32 v[116:117], v[70:71], v[78:79] op_sel_hi:[0,1]
	v_pk_fma_f32 v[110:111], v[114:115], v[50:51], 0 op_sel_hi:[1,1,0]
	v_pk_fma_f32 v[112:113], v[114:115], v[66:67], 0 op_sel_hi:[1,1,0]
	v_pk_mul_f32 v[118:119], v[70:71], v[80:81] op_sel_hi:[0,1]
	ds_read_b128 v[30:33], v94 offset:3200
	v_pk_fma_f32 v[110:111], v[116:117], v[52:53], v[110:111]
	v_pk_fma_f32 v[112:113], v[116:117], v[68:69], v[112:113]
	v_pk_mul_f32 v[120:121], v[70:71], v[82:83] op_sel_hi:[0,1]
	ds_read_b128 v[26:29], v94 offset:3216
	v_pk_fma_f32 v[110:111], v[118:119], v[46:47], v[110:111]
	v_pk_fma_f32 v[112:113], v[118:119], v[62:63], v[112:113]
	v_pk_mul_f32 v[122:123], v[70:71], v[84:85] op_sel_hi:[0,1]
	ds_read_b128 v[22:25], v94 offset:3232
	v_pk_fma_f32 v[110:111], v[120:121], v[48:49], v[110:111]
	v_pk_fma_f32 v[112:113], v[120:121], v[64:65], v[112:113]
	v_pk_mul_f32 v[124:125], v[70:71], v[86:87] op_sel_hi:[0,1]
	ds_read_b128 v[18:21], v94 offset:3248
	v_pk_fma_f32 v[110:111], v[122:123], v[42:43], v[110:111]
	v_pk_fma_f32 v[112:113], v[122:123], v[58:59], v[112:113]
	v_pk_mul_f32 v[126:127], v[70:71], v[88:89] op_sel_hi:[0,1]
	ds_read_b128 v[2:5], v94 offset:3456
	v_pk_fma_f32 v[110:111], v[124:125], v[44:45], v[110:111]
	v_pk_fma_f32 v[112:113], v[124:125], v[60:61], v[112:113]
	v_pk_mul_f32 v[128:129], v[70:71], v[90:91] op_sel_hi:[0,1]
	ds_read_b128 v[6:9], v94 offset:3472
	v_pk_fma_f32 v[110:111], v[126:127], v[38:39], v[110:111]
	v_pk_fma_f32 v[112:113], v[126:127], v[54:55], v[112:113]
	ds_read_b128 v[14:17], v94 offset:3488
	v_pk_fma_f32 v[110:111], v[128:129], v[40:41], v[110:111]
	v_pk_fma_f32 v[112:113], v[128:129], v[56:57], v[112:113]
	ds_read_b128 v[10:13], v94 offset:3504
	v_add_f32_e32 v134, v110, v111
	v_add_f32_e32 v135, v112, v113
	ds_read_b32 v73, v95 offset:3712
	v_add_f32_dpp v134, v134, v134 quad_perm:[1,0,3,2] row_mask:0xf bank_mask:0xf bound_ctrl:1
	v_add_f32_dpp v135, v135, v135 quad_perm:[1,0,3,2] row_mask:0xf bank_mask:0xf bound_ctrl:1
	ds_read_b96 v[34:36], v1 offset:3968
	v_add_f32_dpp v134, v134, v134 quad_perm:[2,3,0,1] row_mask:0xf bank_mask:0xf bound_ctrl:1
	v_add_f32_dpp v135, v135, v135 quad_perm:[2,3,0,1] row_mask:0xf bank_mask:0xf bound_ctrl:1
	v_sub_f32_e32 v134, v0, v134
	v_mul_f32_e32 v134, v71, v134
	v_fma_f32 v135, v72, v134, v135
	v_cvt_pk_bf16_f32 v133, v135, v135
	v_pk_fma_f32 v[74:75], v[50:51], v[134:135], v[114:115] op_sel_hi:[1,0,1]
	v_pk_fma_f32 v[78:79], v[52:53], v[134:135], v[116:117] op_sel_hi:[1,0,1]
	global_store_short v147, v133, s[100:101]
	v_pk_fma_f32 v[80:81], v[46:47], v[134:135], v[118:119] op_sel_hi:[1,0,1]
	v_pk_fma_f32 v[82:83], v[48:49], v[134:135], v[120:121] op_sel_hi:[1,0,1]
	v_pk_fma_f32 v[84:85], v[42:43], v[134:135], v[122:123] op_sel_hi:[1,0,1]
	v_pk_fma_f32 v[86:87], v[44:45], v[134:135], v[124:125] op_sel_hi:[1,0,1]
	v_pk_fma_f32 v[88:89], v[38:39], v[134:135], v[126:127] op_sel_hi:[1,0,1]
	v_pk_fma_f32 v[90:91], v[40:41], v[134:135], v[128:129] op_sel_hi:[1,0,1]
	s_waitcnt lgkmcnt(0)
	v_pk_mul_f32 v[114:115], v[34:35], v[74:75] op_sel_hi:[0,1]
	v_pk_mul_f32 v[116:117], v[34:35], v[78:79] op_sel_hi:[0,1]
	v_pk_fma_f32 v[106:107], v[114:115], v[2:3], 0 op_sel_hi:[1,1,0]
	v_pk_fma_f32 v[108:109], v[114:115], v[30:31], 0 op_sel_hi:[1,1,0]
	v_pk_mul_f32 v[118:119], v[34:35], v[80:81] op_sel_hi:[0,1]
	ds_read_b128 v[66:69], v94 offset:4000
	v_pk_fma_f32 v[106:107], v[116:117], v[4:5], v[106:107]
	v_pk_fma_f32 v[108:109], v[116:117], v[32:33], v[108:109]
	v_pk_mul_f32 v[120:121], v[34:35], v[82:83] op_sel_hi:[0,1]
	ds_read_b128 v[62:65], v94 offset:4016
	v_pk_fma_f32 v[106:107], v[118:119], v[6:7], v[106:107]
	v_pk_fma_f32 v[108:109], v[118:119], v[26:27], v[108:109]
	v_pk_mul_f32 v[122:123], v[34:35], v[84:85] op_sel_hi:[0,1]
	ds_read_b128 v[58:61], v94 offset:4032
	v_pk_fma_f32 v[106:107], v[120:121], v[8:9], v[106:107]
	v_pk_fma_f32 v[108:109], v[120:121], v[28:29], v[108:109]
	v_pk_mul_f32 v[124:125], v[34:35], v[86:87] op_sel_hi:[0,1]
	ds_read_b128 v[54:57], v94 offset:4048
	v_pk_fma_f32 v[106:107], v[122:123], v[14:15], v[106:107]
	v_pk_fma_f32 v[108:109], v[122:123], v[22:23], v[108:109]
	v_pk_mul_f32 v[126:127], v[34:35], v[88:89] op_sel_hi:[0,1]
	ds_read_b128 v[50:53], v94 offset:4256
	v_pk_fma_f32 v[106:107], v[124:125], v[16:17], v[106:107]
	v_pk_fma_f32 v[108:109], v[124:125], v[24:25], v[108:109]
	v_pk_mul_f32 v[128:129], v[34:35], v[90:91] op_sel_hi:[0,1]
	ds_read_b128 v[46:49], v94 offset:4272
	v_pk_fma_f32 v[106:107], v[126:127], v[10:11], v[106:107]
	v_pk_fma_f32 v[108:109], v[126:127], v[18:19], v[108:109]
	ds_read_b128 v[42:45], v94 offset:4288
	v_pk_fma_f32 v[106:107], v[128:129], v[12:13], v[106:107]
	v_pk_fma_f32 v[108:109], v[128:129], v[20:21], v[108:109]
	ds_read_b128 v[38:41], v94 offset:4304
	v_add_f32_e32 v130, v106, v107
	v_add_f32_e32 v131, v108, v109
	ds_read_b32 v0, v95 offset:4512
	v_add_f32_dpp v130, v130, v130 quad_perm:[1,0,3,2] row_mask:0xf bank_mask:0xf bound_ctrl:1
	v_add_f32_dpp v131, v131, v131 quad_perm:[1,0,3,2] row_mask:0xf bank_mask:0xf bound_ctrl:1
	ds_read_b96 v[70:72], v1 offset:4768
	v_add_f32_dpp v130, v130, v130 quad_perm:[2,3,0,1] row_mask:0xf bank_mask:0xf bound_ctrl:1
	v_add_f32_dpp v131, v131, v131 quad_perm:[2,3,0,1] row_mask:0xf bank_mask:0xf bound_ctrl:1
	v_sub_f32_e32 v130, v73, v130
	v_mul_f32_e32 v130, v35, v130
	v_fma_f32 v131, v36, v130, v131
	v_cvt_pk_bf16_f32 v132, v131, v131
	v_pk_fma_f32 v[74:75], v[2:3], v[130:131], v[114:115] op_sel_hi:[1,0,1]
	v_pk_fma_f32 v[78:79], v[4:5], v[130:131], v[116:117] op_sel_hi:[1,0,1]
	global_store_short v148, v132, s[100:101]
	v_pk_fma_f32 v[80:81], v[6:7], v[130:131], v[118:119] op_sel_hi:[1,0,1]
	v_pk_fma_f32 v[82:83], v[8:9], v[130:131], v[120:121] op_sel_hi:[1,0,1]
	v_pk_fma_f32 v[84:85], v[14:15], v[130:131], v[122:123] op_sel_hi:[1,0,1]
	v_pk_fma_f32 v[86:87], v[16:17], v[130:131], v[124:125] op_sel_hi:[1,0,1]
	v_pk_fma_f32 v[88:89], v[10:11], v[130:131], v[126:127] op_sel_hi:[1,0,1]
	v_pk_fma_f32 v[90:91], v[12:13], v[130:131], v[128:129] op_sel_hi:[1,0,1]
	s_waitcnt lgkmcnt(0)
	v_pk_mul_f32 v[114:115], v[70:71], v[74:75] op_sel_hi:[0,1]
	v_pk_mul_f32 v[116:117], v[70:71], v[78:79] op_sel_hi:[0,1]
	v_pk_fma_f32 v[110:111], v[114:115], v[50:51], 0 op_sel_hi:[1,1,0]
	v_pk_fma_f32 v[112:113], v[114:115], v[66:67], 0 op_sel_hi:[1,1,0]
	v_pk_mul_f32 v[118:119], v[70:71], v[80:81] op_sel_hi:[0,1]
	ds_read_b128 v[30:33], v94 offset:4800
	v_pk_fma_f32 v[110:111], v[116:117], v[52:53], v[110:111]
	v_pk_fma_f32 v[112:113], v[116:117], v[68:69], v[112:113]
	v_pk_mul_f32 v[120:121], v[70:71], v[82:83] op_sel_hi:[0,1]
	ds_read_b128 v[26:29], v94 offset:4816
	v_pk_fma_f32 v[110:111], v[118:119], v[46:47], v[110:111]
	v_pk_fma_f32 v[112:113], v[118:119], v[62:63], v[112:113]
	v_pk_mul_f32 v[122:123], v[70:71], v[84:85] op_sel_hi:[0,1]
	ds_read_b128 v[22:25], v94 offset:4832
	v_pk_fma_f32 v[110:111], v[120:121], v[48:49], v[110:111]
	v_pk_fma_f32 v[112:113], v[120:121], v[64:65], v[112:113]
	v_pk_mul_f32 v[124:125], v[70:71], v[86:87] op_sel_hi:[0,1]
	ds_read_b128 v[18:21], v94 offset:4848
	v_pk_fma_f32 v[110:111], v[122:123], v[42:43], v[110:111]
	v_pk_fma_f32 v[112:113], v[122:123], v[58:59], v[112:113]
	v_pk_mul_f32 v[126:127], v[70:71], v[88:89] op_sel_hi:[0,1]
	ds_read_b128 v[2:5], v94 offset:5056
	v_pk_fma_f32 v[110:111], v[124:125], v[44:45], v[110:111]
	v_pk_fma_f32 v[112:113], v[124:125], v[60:61], v[112:113]
	v_pk_mul_f32 v[128:129], v[70:71], v[90:91] op_sel_hi:[0,1]
	ds_read_b128 v[6:9], v94 offset:5072
	v_pk_fma_f32 v[110:111], v[126:127], v[38:39], v[110:111]
	v_pk_fma_f32 v[112:113], v[126:127], v[54:55], v[112:113]
	ds_read_b128 v[14:17], v94 offset:5088
	v_pk_fma_f32 v[110:111], v[128:129], v[40:41], v[110:111]
	v_pk_fma_f32 v[112:113], v[128:129], v[56:57], v[112:113]
	ds_read_b128 v[10:13], v94 offset:5104
	v_add_f32_e32 v134, v110, v111
	v_add_f32_e32 v135, v112, v113
	ds_read_b32 v73, v95 offset:5312
	v_add_f32_dpp v134, v134, v134 quad_perm:[1,0,3,2] row_mask:0xf bank_mask:0xf bound_ctrl:1
	v_add_f32_dpp v135, v135, v135 quad_perm:[1,0,3,2] row_mask:0xf bank_mask:0xf bound_ctrl:1
	ds_read_b96 v[34:36], v1 offset:5568
	v_add_f32_dpp v134, v134, v134 quad_perm:[2,3,0,1] row_mask:0xf bank_mask:0xf bound_ctrl:1
	v_add_f32_dpp v135, v135, v135 quad_perm:[2,3,0,1] row_mask:0xf bank_mask:0xf bound_ctrl:1
	v_sub_f32_e32 v134, v0, v134
	v_mul_f32_e32 v134, v71, v134
	v_fma_f32 v135, v72, v134, v135
	v_cvt_pk_bf16_f32 v133, v135, v135
	v_pk_fma_f32 v[74:75], v[50:51], v[134:135], v[114:115] op_sel_hi:[1,0,1]
	v_pk_fma_f32 v[78:79], v[52:53], v[134:135], v[116:117] op_sel_hi:[1,0,1]
	global_store_short v149, v133, s[100:101]
	v_pk_fma_f32 v[80:81], v[46:47], v[134:135], v[118:119] op_sel_hi:[1,0,1]
	v_pk_fma_f32 v[82:83], v[48:49], v[134:135], v[120:121] op_sel_hi:[1,0,1]
	v_pk_fma_f32 v[84:85], v[42:43], v[134:135], v[122:123] op_sel_hi:[1,0,1]
	v_pk_fma_f32 v[86:87], v[44:45], v[134:135], v[124:125] op_sel_hi:[1,0,1]
	v_pk_fma_f32 v[88:89], v[38:39], v[134:135], v[126:127] op_sel_hi:[1,0,1]
	v_pk_fma_f32 v[90:91], v[40:41], v[134:135], v[128:129] op_sel_hi:[1,0,1]
	s_waitcnt lgkmcnt(0)
	v_pk_mul_f32 v[114:115], v[34:35], v[74:75] op_sel_hi:[0,1]
	v_pk_mul_f32 v[116:117], v[34:35], v[78:79] op_sel_hi:[0,1]
	v_pk_fma_f32 v[106:107], v[114:115], v[2:3], 0 op_sel_hi:[1,1,0]
	v_pk_fma_f32 v[108:109], v[114:115], v[30:31], 0 op_sel_hi:[1,1,0]
	v_pk_mul_f32 v[118:119], v[34:35], v[80:81] op_sel_hi:[0,1]
	ds_read_b128 v[66:69], v94 offset:5600
	v_pk_fma_f32 v[106:107], v[116:117], v[4:5], v[106:107]
	v_pk_fma_f32 v[108:109], v[116:117], v[32:33], v[108:109]
	v_pk_mul_f32 v[120:121], v[34:35], v[82:83] op_sel_hi:[0,1]
	ds_read_b128 v[62:65], v94 offset:5616
	v_pk_fma_f32 v[106:107], v[118:119], v[6:7], v[106:107]
	v_pk_fma_f32 v[108:109], v[118:119], v[26:27], v[108:109]
	v_pk_mul_f32 v[122:123], v[34:35], v[84:85] op_sel_hi:[0,1]
	ds_read_b128 v[58:61], v94 offset:5632
	v_pk_fma_f32 v[106:107], v[120:121], v[8:9], v[106:107]
	v_pk_fma_f32 v[108:109], v[120:121], v[28:29], v[108:109]
	v_pk_mul_f32 v[124:125], v[34:35], v[86:87] op_sel_hi:[0,1]
	ds_read_b128 v[54:57], v94 offset:5648
	v_pk_fma_f32 v[106:107], v[122:123], v[14:15], v[106:107]
	v_pk_fma_f32 v[108:109], v[122:123], v[22:23], v[108:109]
	v_pk_mul_f32 v[126:127], v[34:35], v[88:89] op_sel_hi:[0,1]
	ds_read_b128 v[50:53], v94 offset:5856
	v_pk_fma_f32 v[106:107], v[124:125], v[16:17], v[106:107]
	v_pk_fma_f32 v[108:109], v[124:125], v[24:25], v[108:109]
	v_pk_mul_f32 v[128:129], v[34:35], v[90:91] op_sel_hi:[0,1]
	ds_read_b128 v[46:49], v94 offset:5872
	v_pk_fma_f32 v[106:107], v[126:127], v[10:11], v[106:107]
	v_pk_fma_f32 v[108:109], v[126:127], v[18:19], v[108:109]
	ds_read_b128 v[42:45], v94 offset:5888
	v_pk_fma_f32 v[106:107], v[128:129], v[12:13], v[106:107]
	v_pk_fma_f32 v[108:109], v[128:129], v[20:21], v[108:109]
	ds_read_b128 v[38:41], v94 offset:5904
	v_add_f32_e32 v130, v106, v107
	v_add_f32_e32 v131, v108, v109
	ds_read_b32 v0, v95 offset:6112
	v_add_f32_dpp v130, v130, v130 quad_perm:[1,0,3,2] row_mask:0xf bank_mask:0xf bound_ctrl:1
	v_add_f32_dpp v131, v131, v131 quad_perm:[1,0,3,2] row_mask:0xf bank_mask:0xf bound_ctrl:1
	ds_read_b96 v[70:72], v1 offset:6368
	v_add_f32_dpp v130, v130, v130 quad_perm:[2,3,0,1] row_mask:0xf bank_mask:0xf bound_ctrl:1
	v_add_f32_dpp v131, v131, v131 quad_perm:[2,3,0,1] row_mask:0xf bank_mask:0xf bound_ctrl:1
	v_sub_f32_e32 v130, v73, v130
	v_mul_f32_e32 v130, v35, v130
	v_fma_f32 v131, v36, v130, v131
	v_cvt_pk_bf16_f32 v132, v131, v131
	v_pk_fma_f32 v[74:75], v[2:3], v[130:131], v[114:115] op_sel_hi:[1,0,1]
	v_pk_fma_f32 v[78:79], v[4:5], v[130:131], v[116:117] op_sel_hi:[1,0,1]
	global_store_short v150, v132, s[100:101]
	v_pk_fma_f32 v[80:81], v[6:7], v[130:131], v[118:119] op_sel_hi:[1,0,1]
	v_pk_fma_f32 v[82:83], v[8:9], v[130:131], v[120:121] op_sel_hi:[1,0,1]
	v_pk_fma_f32 v[84:85], v[14:15], v[130:131], v[122:123] op_sel_hi:[1,0,1]
	v_pk_fma_f32 v[86:87], v[16:17], v[130:131], v[124:125] op_sel_hi:[1,0,1]
	v_pk_fma_f32 v[88:89], v[10:11], v[130:131], v[126:127] op_sel_hi:[1,0,1]
	v_pk_fma_f32 v[90:91], v[12:13], v[130:131], v[128:129] op_sel_hi:[1,0,1]
	s_waitcnt lgkmcnt(0)
	v_pk_mul_f32 v[114:115], v[70:71], v[74:75] op_sel_hi:[0,1]
	v_pk_mul_f32 v[116:117], v[70:71], v[78:79] op_sel_hi:[0,1]
	v_pk_fma_f32 v[110:111], v[114:115], v[50:51], 0 op_sel_hi:[1,1,0]
	v_pk_fma_f32 v[112:113], v[114:115], v[66:67], 0 op_sel_hi:[1,1,0]
	v_pk_mul_f32 v[118:119], v[70:71], v[80:81] op_sel_hi:[0,1]
	ds_read_b128 v[30:33], v94 offset:6400
	v_pk_fma_f32 v[110:111], v[116:117], v[52:53], v[110:111]
	v_pk_fma_f32 v[112:113], v[116:117], v[68:69], v[112:113]
	v_pk_mul_f32 v[120:121], v[70:71], v[82:83] op_sel_hi:[0,1]
	ds_read_b128 v[26:29], v94 offset:6416
	v_pk_fma_f32 v[110:111], v[118:119], v[46:47], v[110:111]
	v_pk_fma_f32 v[112:113], v[118:119], v[62:63], v[112:113]
	v_pk_mul_f32 v[122:123], v[70:71], v[84:85] op_sel_hi:[0,1]
	ds_read_b128 v[22:25], v94 offset:6432
	v_pk_fma_f32 v[110:111], v[120:121], v[48:49], v[110:111]
	v_pk_fma_f32 v[112:113], v[120:121], v[64:65], v[112:113]
	v_pk_mul_f32 v[124:125], v[70:71], v[86:87] op_sel_hi:[0,1]
	ds_read_b128 v[18:21], v94 offset:6448
	v_pk_fma_f32 v[110:111], v[122:123], v[42:43], v[110:111]
	v_pk_fma_f32 v[112:113], v[122:123], v[58:59], v[112:113]
	v_pk_mul_f32 v[126:127], v[70:71], v[88:89] op_sel_hi:[0,1]
	ds_read_b128 v[2:5], v94 offset:6656
	v_pk_fma_f32 v[110:111], v[124:125], v[44:45], v[110:111]
	v_pk_fma_f32 v[112:113], v[124:125], v[60:61], v[112:113]
	v_pk_mul_f32 v[128:129], v[70:71], v[90:91] op_sel_hi:[0,1]
	ds_read_b128 v[6:9], v94 offset:6672
	v_pk_fma_f32 v[110:111], v[126:127], v[38:39], v[110:111]
	v_pk_fma_f32 v[112:113], v[126:127], v[54:55], v[112:113]
	ds_read_b128 v[14:17], v94 offset:6688
	v_pk_fma_f32 v[110:111], v[128:129], v[40:41], v[110:111]
	v_pk_fma_f32 v[112:113], v[128:129], v[56:57], v[112:113]
	ds_read_b128 v[10:13], v94 offset:6704
	v_add_f32_e32 v134, v110, v111
	v_add_f32_e32 v135, v112, v113
	ds_read_b32 v73, v95 offset:6912
	v_add_f32_dpp v134, v134, v134 quad_perm:[1,0,3,2] row_mask:0xf bank_mask:0xf bound_ctrl:1
	v_add_f32_dpp v135, v135, v135 quad_perm:[1,0,3,2] row_mask:0xf bank_mask:0xf bound_ctrl:1
	ds_read_b96 v[34:36], v1 offset:7168
	v_add_f32_dpp v134, v134, v134 quad_perm:[2,3,0,1] row_mask:0xf bank_mask:0xf bound_ctrl:1
	v_add_f32_dpp v135, v135, v135 quad_perm:[2,3,0,1] row_mask:0xf bank_mask:0xf bound_ctrl:1
	v_sub_f32_e32 v134, v0, v134
	v_mul_f32_e32 v134, v71, v134
	v_fma_f32 v135, v72, v134, v135
	v_cvt_pk_bf16_f32 v133, v135, v135
	v_pk_fma_f32 v[74:75], v[50:51], v[134:135], v[114:115] op_sel_hi:[1,0,1]
	v_pk_fma_f32 v[78:79], v[52:53], v[134:135], v[116:117] op_sel_hi:[1,0,1]
	global_store_short v151, v133, s[100:101]
	v_pk_fma_f32 v[80:81], v[46:47], v[134:135], v[118:119] op_sel_hi:[1,0,1]
	v_pk_fma_f32 v[82:83], v[48:49], v[134:135], v[120:121] op_sel_hi:[1,0,1]
	v_pk_fma_f32 v[84:85], v[42:43], v[134:135], v[122:123] op_sel_hi:[1,0,1]
	v_pk_fma_f32 v[86:87], v[44:45], v[134:135], v[124:125] op_sel_hi:[1,0,1]
	v_pk_fma_f32 v[88:89], v[38:39], v[134:135], v[126:127] op_sel_hi:[1,0,1]
	v_pk_fma_f32 v[90:91], v[40:41], v[134:135], v[128:129] op_sel_hi:[1,0,1]
	s_waitcnt lgkmcnt(0)
	v_pk_mul_f32 v[114:115], v[34:35], v[74:75] op_sel_hi:[0,1]
	v_pk_mul_f32 v[116:117], v[34:35], v[78:79] op_sel_hi:[0,1]
	v_pk_fma_f32 v[106:107], v[114:115], v[2:3], 0 op_sel_hi:[1,1,0]
	v_pk_fma_f32 v[108:109], v[114:115], v[30:31], 0 op_sel_hi:[1,1,0]
	v_pk_mul_f32 v[118:119], v[34:35], v[80:81] op_sel_hi:[0,1]
	ds_read_b128 v[66:69], v94 offset:7200
	v_pk_fma_f32 v[106:107], v[116:117], v[4:5], v[106:107]
	v_pk_fma_f32 v[108:109], v[116:117], v[32:33], v[108:109]
	v_pk_mul_f32 v[120:121], v[34:35], v[82:83] op_sel_hi:[0,1]
	ds_read_b128 v[62:65], v94 offset:7216
	v_pk_fma_f32 v[106:107], v[118:119], v[6:7], v[106:107]
	v_pk_fma_f32 v[108:109], v[118:119], v[26:27], v[108:109]
	v_pk_mul_f32 v[122:123], v[34:35], v[84:85] op_sel_hi:[0,1]
	ds_read_b128 v[58:61], v94 offset:7232
	v_pk_fma_f32 v[106:107], v[120:121], v[8:9], v[106:107]
	v_pk_fma_f32 v[108:109], v[120:121], v[28:29], v[108:109]
	v_pk_mul_f32 v[124:125], v[34:35], v[86:87] op_sel_hi:[0,1]
	ds_read_b128 v[54:57], v94 offset:7248
	v_pk_fma_f32 v[106:107], v[122:123], v[14:15], v[106:107]
	v_pk_fma_f32 v[108:109], v[122:123], v[22:23], v[108:109]
	v_pk_mul_f32 v[126:127], v[34:35], v[88:89] op_sel_hi:[0,1]
	ds_read_b128 v[50:53], v94 offset:7456
	v_pk_fma_f32 v[106:107], v[124:125], v[16:17], v[106:107]
	v_pk_fma_f32 v[108:109], v[124:125], v[24:25], v[108:109]
	v_pk_mul_f32 v[128:129], v[34:35], v[90:91] op_sel_hi:[0,1]
	ds_read_b128 v[46:49], v94 offset:7472
	v_pk_fma_f32 v[106:107], v[126:127], v[10:11], v[106:107]
	v_pk_fma_f32 v[108:109], v[126:127], v[18:19], v[108:109]
	ds_read_b128 v[42:45], v94 offset:7488
	v_pk_fma_f32 v[106:107], v[128:129], v[12:13], v[106:107]
	v_pk_fma_f32 v[108:109], v[128:129], v[20:21], v[108:109]
	ds_read_b128 v[38:41], v94 offset:7504
	v_add_f32_e32 v130, v106, v107
	v_add_f32_e32 v131, v108, v109
	ds_read_b32 v0, v95 offset:7712
	v_add_f32_dpp v130, v130, v130 quad_perm:[1,0,3,2] row_mask:0xf bank_mask:0xf bound_ctrl:1
	v_add_f32_dpp v131, v131, v131 quad_perm:[1,0,3,2] row_mask:0xf bank_mask:0xf bound_ctrl:1
	ds_read_b96 v[70:72], v1 offset:7968
	v_add_f32_dpp v130, v130, v130 quad_perm:[2,3,0,1] row_mask:0xf bank_mask:0xf bound_ctrl:1
	v_add_f32_dpp v131, v131, v131 quad_perm:[2,3,0,1] row_mask:0xf bank_mask:0xf bound_ctrl:1
	v_sub_f32_e32 v130, v73, v130
	v_mul_f32_e32 v130, v35, v130
	v_fma_f32 v131, v36, v130, v131
	v_cvt_pk_bf16_f32 v132, v131, v131
	v_pk_fma_f32 v[74:75], v[2:3], v[130:131], v[114:115] op_sel_hi:[1,0,1]
	v_pk_fma_f32 v[78:79], v[4:5], v[130:131], v[116:117] op_sel_hi:[1,0,1]
	global_store_short v152, v132, s[100:101]
	v_pk_fma_f32 v[80:81], v[6:7], v[130:131], v[118:119] op_sel_hi:[1,0,1]
	v_pk_fma_f32 v[82:83], v[8:9], v[130:131], v[120:121] op_sel_hi:[1,0,1]
	v_pk_fma_f32 v[84:85], v[14:15], v[130:131], v[122:123] op_sel_hi:[1,0,1]
	v_pk_fma_f32 v[86:87], v[16:17], v[130:131], v[124:125] op_sel_hi:[1,0,1]
	v_pk_fma_f32 v[88:89], v[10:11], v[130:131], v[126:127] op_sel_hi:[1,0,1]
	v_pk_fma_f32 v[90:91], v[12:13], v[130:131], v[128:129] op_sel_hi:[1,0,1]
	s_waitcnt lgkmcnt(0)
	v_pk_mul_f32 v[114:115], v[70:71], v[74:75] op_sel_hi:[0,1]
	v_pk_mul_f32 v[116:117], v[70:71], v[78:79] op_sel_hi:[0,1]
	v_pk_fma_f32 v[110:111], v[114:115], v[50:51], 0 op_sel_hi:[1,1,0]
	v_pk_fma_f32 v[112:113], v[114:115], v[66:67], 0 op_sel_hi:[1,1,0]
	v_pk_mul_f32 v[118:119], v[70:71], v[80:81] op_sel_hi:[0,1]
	ds_read_b128 v[30:33], v94 offset:8000
	v_pk_fma_f32 v[110:111], v[116:117], v[52:53], v[110:111]
	v_pk_fma_f32 v[112:113], v[116:117], v[68:69], v[112:113]
	v_pk_mul_f32 v[120:121], v[70:71], v[82:83] op_sel_hi:[0,1]
	ds_read_b128 v[26:29], v94 offset:8016
	v_pk_fma_f32 v[110:111], v[118:119], v[46:47], v[110:111]
	v_pk_fma_f32 v[112:113], v[118:119], v[62:63], v[112:113]
	v_pk_mul_f32 v[122:123], v[70:71], v[84:85] op_sel_hi:[0,1]
	ds_read_b128 v[22:25], v94 offset:8032
	v_pk_fma_f32 v[110:111], v[120:121], v[48:49], v[110:111]
	v_pk_fma_f32 v[112:113], v[120:121], v[64:65], v[112:113]
	v_pk_mul_f32 v[124:125], v[70:71], v[86:87] op_sel_hi:[0,1]
	ds_read_b128 v[18:21], v94 offset:8048
	v_pk_fma_f32 v[110:111], v[122:123], v[42:43], v[110:111]
	v_pk_fma_f32 v[112:113], v[122:123], v[58:59], v[112:113]
	v_pk_mul_f32 v[126:127], v[70:71], v[88:89] op_sel_hi:[0,1]
	ds_read_b128 v[2:5], v94 offset:8256
	v_pk_fma_f32 v[110:111], v[124:125], v[44:45], v[110:111]
	v_pk_fma_f32 v[112:113], v[124:125], v[60:61], v[112:113]
	v_pk_mul_f32 v[128:129], v[70:71], v[90:91] op_sel_hi:[0,1]
	ds_read_b128 v[6:9], v94 offset:8272
	v_pk_fma_f32 v[110:111], v[126:127], v[38:39], v[110:111]
	v_pk_fma_f32 v[112:113], v[126:127], v[54:55], v[112:113]
	ds_read_b128 v[14:17], v94 offset:8288
	v_pk_fma_f32 v[110:111], v[128:129], v[40:41], v[110:111]
	v_pk_fma_f32 v[112:113], v[128:129], v[56:57], v[112:113]
	ds_read_b128 v[10:13], v94 offset:8304
	v_add_f32_e32 v134, v110, v111
	v_add_f32_e32 v135, v112, v113
	ds_read_b32 v73, v95 offset:8512
	v_add_f32_dpp v134, v134, v134 quad_perm:[1,0,3,2] row_mask:0xf bank_mask:0xf bound_ctrl:1
	v_add_f32_dpp v135, v135, v135 quad_perm:[1,0,3,2] row_mask:0xf bank_mask:0xf bound_ctrl:1
	ds_read_b96 v[34:36], v1 offset:8768
	v_add_f32_dpp v134, v134, v134 quad_perm:[2,3,0,1] row_mask:0xf bank_mask:0xf bound_ctrl:1
	v_add_f32_dpp v135, v135, v135 quad_perm:[2,3,0,1] row_mask:0xf bank_mask:0xf bound_ctrl:1
	v_sub_f32_e32 v134, v0, v134
	v_mul_f32_e32 v134, v71, v134
	v_fma_f32 v135, v72, v134, v135
	v_cvt_pk_bf16_f32 v133, v135, v135
	v_pk_fma_f32 v[74:75], v[50:51], v[134:135], v[114:115] op_sel_hi:[1,0,1]
	v_pk_fma_f32 v[78:79], v[52:53], v[134:135], v[116:117] op_sel_hi:[1,0,1]
	global_store_short v153, v133, s[100:101]
	v_pk_fma_f32 v[80:81], v[46:47], v[134:135], v[118:119] op_sel_hi:[1,0,1]
	v_pk_fma_f32 v[82:83], v[48:49], v[134:135], v[120:121] op_sel_hi:[1,0,1]
	v_pk_fma_f32 v[84:85], v[42:43], v[134:135], v[122:123] op_sel_hi:[1,0,1]
	v_pk_fma_f32 v[86:87], v[44:45], v[134:135], v[124:125] op_sel_hi:[1,0,1]
	v_pk_fma_f32 v[88:89], v[38:39], v[134:135], v[126:127] op_sel_hi:[1,0,1]
	v_pk_fma_f32 v[90:91], v[40:41], v[134:135], v[128:129] op_sel_hi:[1,0,1]
	s_waitcnt lgkmcnt(0)
	v_pk_mul_f32 v[114:115], v[34:35], v[74:75] op_sel_hi:[0,1]
	v_pk_mul_f32 v[116:117], v[34:35], v[78:79] op_sel_hi:[0,1]
	v_pk_fma_f32 v[106:107], v[114:115], v[2:3], 0 op_sel_hi:[1,1,0]
	v_pk_fma_f32 v[108:109], v[114:115], v[30:31], 0 op_sel_hi:[1,1,0]
	v_pk_mul_f32 v[118:119], v[34:35], v[80:81] op_sel_hi:[0,1]
	ds_read_b128 v[66:69], v94 offset:8800
	v_pk_fma_f32 v[106:107], v[116:117], v[4:5], v[106:107]
	v_pk_fma_f32 v[108:109], v[116:117], v[32:33], v[108:109]
	v_pk_mul_f32 v[120:121], v[34:35], v[82:83] op_sel_hi:[0,1]
	ds_read_b128 v[62:65], v94 offset:8816
	v_pk_fma_f32 v[106:107], v[118:119], v[6:7], v[106:107]
	v_pk_fma_f32 v[108:109], v[118:119], v[26:27], v[108:109]
	v_pk_mul_f32 v[122:123], v[34:35], v[84:85] op_sel_hi:[0,1]
	ds_read_b128 v[58:61], v94 offset:8832
	v_pk_fma_f32 v[106:107], v[120:121], v[8:9], v[106:107]
	v_pk_fma_f32 v[108:109], v[120:121], v[28:29], v[108:109]
	v_pk_mul_f32 v[124:125], v[34:35], v[86:87] op_sel_hi:[0,1]
	ds_read_b128 v[54:57], v94 offset:8848
	v_pk_fma_f32 v[106:107], v[122:123], v[14:15], v[106:107]
	v_pk_fma_f32 v[108:109], v[122:123], v[22:23], v[108:109]
	v_pk_mul_f32 v[126:127], v[34:35], v[88:89] op_sel_hi:[0,1]
	ds_read_b128 v[50:53], v94 offset:9056
	v_pk_fma_f32 v[106:107], v[124:125], v[16:17], v[106:107]
	v_pk_fma_f32 v[108:109], v[124:125], v[24:25], v[108:109]
	v_pk_mul_f32 v[128:129], v[34:35], v[90:91] op_sel_hi:[0,1]
	ds_read_b128 v[46:49], v94 offset:9072
	v_pk_fma_f32 v[106:107], v[126:127], v[10:11], v[106:107]
	v_pk_fma_f32 v[108:109], v[126:127], v[18:19], v[108:109]
	ds_read_b128 v[42:45], v94 offset:9088
	v_pk_fma_f32 v[106:107], v[128:129], v[12:13], v[106:107]
	v_pk_fma_f32 v[108:109], v[128:129], v[20:21], v[108:109]
	ds_read_b128 v[38:41], v94 offset:9104
	v_add_f32_e32 v130, v106, v107
	v_add_f32_e32 v131, v108, v109
	ds_read_b32 v0, v95 offset:9312
	v_add_f32_dpp v130, v130, v130 quad_perm:[1,0,3,2] row_mask:0xf bank_mask:0xf bound_ctrl:1
	v_add_f32_dpp v131, v131, v131 quad_perm:[1,0,3,2] row_mask:0xf bank_mask:0xf bound_ctrl:1
	ds_read_b96 v[70:72], v1 offset:9568
	v_add_f32_dpp v130, v130, v130 quad_perm:[2,3,0,1] row_mask:0xf bank_mask:0xf bound_ctrl:1
	v_add_f32_dpp v131, v131, v131 quad_perm:[2,3,0,1] row_mask:0xf bank_mask:0xf bound_ctrl:1
	v_sub_f32_e32 v130, v73, v130
	v_mul_f32_e32 v130, v35, v130
	v_fma_f32 v131, v36, v130, v131
	v_cvt_pk_bf16_f32 v132, v131, v131
	v_pk_fma_f32 v[74:75], v[2:3], v[130:131], v[114:115] op_sel_hi:[1,0,1]
	v_pk_fma_f32 v[78:79], v[4:5], v[130:131], v[116:117] op_sel_hi:[1,0,1]
	global_store_short v154, v132, s[100:101]
	v_pk_fma_f32 v[80:81], v[6:7], v[130:131], v[118:119] op_sel_hi:[1,0,1]
	v_pk_fma_f32 v[82:83], v[8:9], v[130:131], v[120:121] op_sel_hi:[1,0,1]
	v_pk_fma_f32 v[84:85], v[14:15], v[130:131], v[122:123] op_sel_hi:[1,0,1]
	v_pk_fma_f32 v[86:87], v[16:17], v[130:131], v[124:125] op_sel_hi:[1,0,1]
	v_pk_fma_f32 v[88:89], v[10:11], v[130:131], v[126:127] op_sel_hi:[1,0,1]
	v_pk_fma_f32 v[90:91], v[12:13], v[130:131], v[128:129] op_sel_hi:[1,0,1]
	s_waitcnt lgkmcnt(0)
	v_pk_mul_f32 v[114:115], v[70:71], v[74:75] op_sel_hi:[0,1]
	v_pk_mul_f32 v[116:117], v[70:71], v[78:79] op_sel_hi:[0,1]
	v_pk_fma_f32 v[110:111], v[114:115], v[50:51], 0 op_sel_hi:[1,1,0]
	v_pk_fma_f32 v[112:113], v[114:115], v[66:67], 0 op_sel_hi:[1,1,0]
	v_pk_mul_f32 v[118:119], v[70:71], v[80:81] op_sel_hi:[0,1]
	ds_read_b128 v[30:33], v94 offset:9600
	v_pk_fma_f32 v[110:111], v[116:117], v[52:53], v[110:111]
	v_pk_fma_f32 v[112:113], v[116:117], v[68:69], v[112:113]
	v_pk_mul_f32 v[120:121], v[70:71], v[82:83] op_sel_hi:[0,1]
	ds_read_b128 v[26:29], v94 offset:9616
	v_pk_fma_f32 v[110:111], v[118:119], v[46:47], v[110:111]
	v_pk_fma_f32 v[112:113], v[118:119], v[62:63], v[112:113]
	v_pk_mul_f32 v[122:123], v[70:71], v[84:85] op_sel_hi:[0,1]
	ds_read_b128 v[22:25], v94 offset:9632
	v_pk_fma_f32 v[110:111], v[120:121], v[48:49], v[110:111]
	v_pk_fma_f32 v[112:113], v[120:121], v[64:65], v[112:113]
	v_pk_mul_f32 v[124:125], v[70:71], v[86:87] op_sel_hi:[0,1]
	ds_read_b128 v[18:21], v94 offset:9648
	v_pk_fma_f32 v[110:111], v[122:123], v[42:43], v[110:111]
	v_pk_fma_f32 v[112:113], v[122:123], v[58:59], v[112:113]
	v_pk_mul_f32 v[126:127], v[70:71], v[88:89] op_sel_hi:[0,1]
	ds_read_b128 v[2:5], v94 offset:9856
	v_pk_fma_f32 v[110:111], v[124:125], v[44:45], v[110:111]
	v_pk_fma_f32 v[112:113], v[124:125], v[60:61], v[112:113]
	v_pk_mul_f32 v[128:129], v[70:71], v[90:91] op_sel_hi:[0,1]
	ds_read_b128 v[6:9], v94 offset:9872
	v_pk_fma_f32 v[110:111], v[126:127], v[38:39], v[110:111]
	v_pk_fma_f32 v[112:113], v[126:127], v[54:55], v[112:113]
	ds_read_b128 v[14:17], v94 offset:9888
	v_pk_fma_f32 v[110:111], v[128:129], v[40:41], v[110:111]
	v_pk_fma_f32 v[112:113], v[128:129], v[56:57], v[112:113]
	ds_read_b128 v[10:13], v94 offset:9904
	v_add_f32_e32 v134, v110, v111
	v_add_f32_e32 v135, v112, v113
	ds_read_b32 v73, v95 offset:10112
	v_add_f32_dpp v134, v134, v134 quad_perm:[1,0,3,2] row_mask:0xf bank_mask:0xf bound_ctrl:1
	v_add_f32_dpp v135, v135, v135 quad_perm:[1,0,3,2] row_mask:0xf bank_mask:0xf bound_ctrl:1
	ds_read_b96 v[34:36], v1 offset:10368
	v_add_f32_dpp v134, v134, v134 quad_perm:[2,3,0,1] row_mask:0xf bank_mask:0xf bound_ctrl:1
	v_add_f32_dpp v135, v135, v135 quad_perm:[2,3,0,1] row_mask:0xf bank_mask:0xf bound_ctrl:1
	v_sub_f32_e32 v134, v0, v134
	v_mul_f32_e32 v134, v71, v134
	v_fma_f32 v135, v72, v134, v135
	v_cvt_pk_bf16_f32 v133, v135, v135
	v_pk_fma_f32 v[74:75], v[50:51], v[134:135], v[114:115] op_sel_hi:[1,0,1]
	v_pk_fma_f32 v[78:79], v[52:53], v[134:135], v[116:117] op_sel_hi:[1,0,1]
	global_store_short v155, v133, s[100:101]
	v_pk_fma_f32 v[80:81], v[46:47], v[134:135], v[118:119] op_sel_hi:[1,0,1]
	v_pk_fma_f32 v[82:83], v[48:49], v[134:135], v[120:121] op_sel_hi:[1,0,1]
	v_pk_fma_f32 v[84:85], v[42:43], v[134:135], v[122:123] op_sel_hi:[1,0,1]
	v_pk_fma_f32 v[86:87], v[44:45], v[134:135], v[124:125] op_sel_hi:[1,0,1]
	v_pk_fma_f32 v[88:89], v[38:39], v[134:135], v[126:127] op_sel_hi:[1,0,1]
	v_pk_fma_f32 v[90:91], v[40:41], v[134:135], v[128:129] op_sel_hi:[1,0,1]
	s_waitcnt lgkmcnt(0)
	v_pk_mul_f32 v[114:115], v[34:35], v[74:75] op_sel_hi:[0,1]
	v_pk_mul_f32 v[116:117], v[34:35], v[78:79] op_sel_hi:[0,1]
	v_pk_fma_f32 v[106:107], v[114:115], v[2:3], 0 op_sel_hi:[1,1,0]
	v_pk_fma_f32 v[108:109], v[114:115], v[30:31], 0 op_sel_hi:[1,1,0]
	v_pk_mul_f32 v[118:119], v[34:35], v[80:81] op_sel_hi:[0,1]
	ds_read_b128 v[66:69], v94 offset:10400
	v_pk_fma_f32 v[106:107], v[116:117], v[4:5], v[106:107]
	v_pk_fma_f32 v[108:109], v[116:117], v[32:33], v[108:109]
	v_pk_mul_f32 v[120:121], v[34:35], v[82:83] op_sel_hi:[0,1]
	ds_read_b128 v[62:65], v94 offset:10416
	v_pk_fma_f32 v[106:107], v[118:119], v[6:7], v[106:107]
	v_pk_fma_f32 v[108:109], v[118:119], v[26:27], v[108:109]
	v_pk_mul_f32 v[122:123], v[34:35], v[84:85] op_sel_hi:[0,1]
	ds_read_b128 v[58:61], v94 offset:10432
	v_pk_fma_f32 v[106:107], v[120:121], v[8:9], v[106:107]
	v_pk_fma_f32 v[108:109], v[120:121], v[28:29], v[108:109]
	v_pk_mul_f32 v[124:125], v[34:35], v[86:87] op_sel_hi:[0,1]
	ds_read_b128 v[54:57], v94 offset:10448
	v_pk_fma_f32 v[106:107], v[122:123], v[14:15], v[106:107]
	v_pk_fma_f32 v[108:109], v[122:123], v[22:23], v[108:109]
	v_pk_mul_f32 v[126:127], v[34:35], v[88:89] op_sel_hi:[0,1]
	ds_read_b128 v[50:53], v94 offset:10656
	v_pk_fma_f32 v[106:107], v[124:125], v[16:17], v[106:107]
	v_pk_fma_f32 v[108:109], v[124:125], v[24:25], v[108:109]
	v_pk_mul_f32 v[128:129], v[34:35], v[90:91] op_sel_hi:[0,1]
	ds_read_b128 v[46:49], v94 offset:10672
	v_pk_fma_f32 v[106:107], v[126:127], v[10:11], v[106:107]
	v_pk_fma_f32 v[108:109], v[126:127], v[18:19], v[108:109]
	ds_read_b128 v[42:45], v94 offset:10688
	v_pk_fma_f32 v[106:107], v[128:129], v[12:13], v[106:107]
	v_pk_fma_f32 v[108:109], v[128:129], v[20:21], v[108:109]
	ds_read_b128 v[38:41], v94 offset:10704
	v_add_f32_e32 v130, v106, v107
	v_add_f32_e32 v131, v108, v109
	ds_read_b32 v0, v95 offset:10912
	v_add_f32_dpp v130, v130, v130 quad_perm:[1,0,3,2] row_mask:0xf bank_mask:0xf bound_ctrl:1
	v_add_f32_dpp v131, v131, v131 quad_perm:[1,0,3,2] row_mask:0xf bank_mask:0xf bound_ctrl:1
	ds_read_b96 v[70:72], v1 offset:11168
	v_add_f32_dpp v130, v130, v130 quad_perm:[2,3,0,1] row_mask:0xf bank_mask:0xf bound_ctrl:1
	v_add_f32_dpp v131, v131, v131 quad_perm:[2,3,0,1] row_mask:0xf bank_mask:0xf bound_ctrl:1
	v_sub_f32_e32 v130, v73, v130
	v_mul_f32_e32 v130, v35, v130
	v_fma_f32 v131, v36, v130, v131
	v_cvt_pk_bf16_f32 v132, v131, v131
	v_pk_fma_f32 v[74:75], v[2:3], v[130:131], v[114:115] op_sel_hi:[1,0,1]
	v_pk_fma_f32 v[78:79], v[4:5], v[130:131], v[116:117] op_sel_hi:[1,0,1]
	global_store_short v156, v132, s[100:101]
	v_pk_fma_f32 v[80:81], v[6:7], v[130:131], v[118:119] op_sel_hi:[1,0,1]
	v_pk_fma_f32 v[82:83], v[8:9], v[130:131], v[120:121] op_sel_hi:[1,0,1]
	v_pk_fma_f32 v[84:85], v[14:15], v[130:131], v[122:123] op_sel_hi:[1,0,1]
	v_pk_fma_f32 v[86:87], v[16:17], v[130:131], v[124:125] op_sel_hi:[1,0,1]
	v_pk_fma_f32 v[88:89], v[10:11], v[130:131], v[126:127] op_sel_hi:[1,0,1]
	v_pk_fma_f32 v[90:91], v[12:13], v[130:131], v[128:129] op_sel_hi:[1,0,1]
	s_waitcnt lgkmcnt(0)
	v_pk_mul_f32 v[114:115], v[70:71], v[74:75] op_sel_hi:[0,1]
	v_pk_mul_f32 v[116:117], v[70:71], v[78:79] op_sel_hi:[0,1]
	v_pk_fma_f32 v[110:111], v[114:115], v[50:51], 0 op_sel_hi:[1,1,0]
	v_pk_fma_f32 v[112:113], v[114:115], v[66:67], 0 op_sel_hi:[1,1,0]
	v_pk_mul_f32 v[118:119], v[70:71], v[80:81] op_sel_hi:[0,1]
	ds_read_b128 v[30:33], v94 offset:11200
	v_pk_fma_f32 v[110:111], v[116:117], v[52:53], v[110:111]
	v_pk_fma_f32 v[112:113], v[116:117], v[68:69], v[112:113]
	v_pk_mul_f32 v[120:121], v[70:71], v[82:83] op_sel_hi:[0,1]
	ds_read_b128 v[26:29], v94 offset:11216
	v_pk_fma_f32 v[110:111], v[118:119], v[46:47], v[110:111]
	v_pk_fma_f32 v[112:113], v[118:119], v[62:63], v[112:113]
	v_pk_mul_f32 v[122:123], v[70:71], v[84:85] op_sel_hi:[0,1]
	ds_read_b128 v[22:25], v94 offset:11232
	v_pk_fma_f32 v[110:111], v[120:121], v[48:49], v[110:111]
	v_pk_fma_f32 v[112:113], v[120:121], v[64:65], v[112:113]
	v_pk_mul_f32 v[124:125], v[70:71], v[86:87] op_sel_hi:[0,1]
	ds_read_b128 v[18:21], v94 offset:11248
	v_pk_fma_f32 v[110:111], v[122:123], v[42:43], v[110:111]
	v_pk_fma_f32 v[112:113], v[122:123], v[58:59], v[112:113]
	v_pk_mul_f32 v[126:127], v[70:71], v[88:89] op_sel_hi:[0,1]
	ds_read_b128 v[2:5], v94 offset:11456
	v_pk_fma_f32 v[110:111], v[124:125], v[44:45], v[110:111]
	v_pk_fma_f32 v[112:113], v[124:125], v[60:61], v[112:113]
	v_pk_mul_f32 v[128:129], v[70:71], v[90:91] op_sel_hi:[0,1]
	ds_read_b128 v[6:9], v94 offset:11472
	v_pk_fma_f32 v[110:111], v[126:127], v[38:39], v[110:111]
	v_pk_fma_f32 v[112:113], v[126:127], v[54:55], v[112:113]
	ds_read_b128 v[14:17], v94 offset:11488
	v_pk_fma_f32 v[110:111], v[128:129], v[40:41], v[110:111]
	v_pk_fma_f32 v[112:113], v[128:129], v[56:57], v[112:113]
	ds_read_b128 v[10:13], v94 offset:11504
	v_add_f32_e32 v134, v110, v111
	v_add_f32_e32 v135, v112, v113
	ds_read_b32 v73, v95 offset:11712
	v_add_f32_dpp v134, v134, v134 quad_perm:[1,0,3,2] row_mask:0xf bank_mask:0xf bound_ctrl:1
	v_add_f32_dpp v135, v135, v135 quad_perm:[1,0,3,2] row_mask:0xf bank_mask:0xf bound_ctrl:1
	ds_read_b96 v[34:36], v1 offset:11968
	v_add_f32_dpp v134, v134, v134 quad_perm:[2,3,0,1] row_mask:0xf bank_mask:0xf bound_ctrl:1
	v_add_f32_dpp v135, v135, v135 quad_perm:[2,3,0,1] row_mask:0xf bank_mask:0xf bound_ctrl:1
	v_sub_f32_e32 v134, v0, v134
	v_mul_f32_e32 v134, v71, v134
	v_fma_f32 v135, v72, v134, v135
	v_cvt_pk_bf16_f32 v133, v135, v135
	v_pk_fma_f32 v[74:75], v[50:51], v[134:135], v[114:115] op_sel_hi:[1,0,1]
	v_pk_fma_f32 v[78:79], v[52:53], v[134:135], v[116:117] op_sel_hi:[1,0,1]
	global_store_short v157, v133, s[100:101]
	v_pk_fma_f32 v[80:81], v[46:47], v[134:135], v[118:119] op_sel_hi:[1,0,1]
	v_pk_fma_f32 v[82:83], v[48:49], v[134:135], v[120:121] op_sel_hi:[1,0,1]
	v_pk_fma_f32 v[84:85], v[42:43], v[134:135], v[122:123] op_sel_hi:[1,0,1]
	v_pk_fma_f32 v[86:87], v[44:45], v[134:135], v[124:125] op_sel_hi:[1,0,1]
	v_pk_fma_f32 v[88:89], v[38:39], v[134:135], v[126:127] op_sel_hi:[1,0,1]
	v_pk_fma_f32 v[90:91], v[40:41], v[134:135], v[128:129] op_sel_hi:[1,0,1]
	s_waitcnt lgkmcnt(0)
	v_pk_mul_f32 v[114:115], v[34:35], v[74:75] op_sel_hi:[0,1]
	v_pk_mul_f32 v[116:117], v[34:35], v[78:79] op_sel_hi:[0,1]
	v_pk_fma_f32 v[106:107], v[114:115], v[2:3], 0 op_sel_hi:[1,1,0]
	v_pk_fma_f32 v[108:109], v[114:115], v[30:31], 0 op_sel_hi:[1,1,0]
	v_pk_mul_f32 v[118:119], v[34:35], v[80:81] op_sel_hi:[0,1]
	ds_read_b128 v[66:69], v94 offset:12000
	v_pk_fma_f32 v[106:107], v[116:117], v[4:5], v[106:107]
	v_pk_fma_f32 v[108:109], v[116:117], v[32:33], v[108:109]
	v_pk_mul_f32 v[120:121], v[34:35], v[82:83] op_sel_hi:[0,1]
	ds_read_b128 v[62:65], v94 offset:12016
	v_pk_fma_f32 v[106:107], v[118:119], v[6:7], v[106:107]
	v_pk_fma_f32 v[108:109], v[118:119], v[26:27], v[108:109]
	v_pk_mul_f32 v[122:123], v[34:35], v[84:85] op_sel_hi:[0,1]
	ds_read_b128 v[58:61], v94 offset:12032
	v_pk_fma_f32 v[106:107], v[120:121], v[8:9], v[106:107]
	v_pk_fma_f32 v[108:109], v[120:121], v[28:29], v[108:109]
	v_pk_mul_f32 v[124:125], v[34:35], v[86:87] op_sel_hi:[0,1]
	ds_read_b128 v[54:57], v94 offset:12048
	v_pk_fma_f32 v[106:107], v[122:123], v[14:15], v[106:107]
	v_pk_fma_f32 v[108:109], v[122:123], v[22:23], v[108:109]
	v_pk_mul_f32 v[126:127], v[34:35], v[88:89] op_sel_hi:[0,1]
	ds_read_b128 v[50:53], v94 offset:12256
	v_pk_fma_f32 v[106:107], v[124:125], v[16:17], v[106:107]
	v_pk_fma_f32 v[108:109], v[124:125], v[24:25], v[108:109]
	v_pk_mul_f32 v[128:129], v[34:35], v[90:91] op_sel_hi:[0,1]
	ds_read_b128 v[46:49], v94 offset:12272
	v_pk_fma_f32 v[106:107], v[126:127], v[10:11], v[106:107]
	v_pk_fma_f32 v[108:109], v[126:127], v[18:19], v[108:109]
	ds_read_b128 v[42:45], v94 offset:12288
	v_pk_fma_f32 v[106:107], v[128:129], v[12:13], v[106:107]
	v_pk_fma_f32 v[108:109], v[128:129], v[20:21], v[108:109]
	ds_read_b128 v[38:41], v94 offset:12304
	v_add_f32_e32 v130, v106, v107
	v_add_f32_e32 v131, v108, v109
	ds_read_b32 v0, v95 offset:12512
	v_add_f32_dpp v130, v130, v130 quad_perm:[1,0,3,2] row_mask:0xf bank_mask:0xf bound_ctrl:1
	v_add_f32_dpp v131, v131, v131 quad_perm:[1,0,3,2] row_mask:0xf bank_mask:0xf bound_ctrl:1
	ds_read_b96 v[70:72], v1 offset:12768
	v_add_f32_dpp v130, v130, v130 quad_perm:[2,3,0,1] row_mask:0xf bank_mask:0xf bound_ctrl:1
	v_add_f32_dpp v131, v131, v131 quad_perm:[2,3,0,1] row_mask:0xf bank_mask:0xf bound_ctrl:1
	v_sub_f32_e32 v130, v73, v130
	v_mul_f32_e32 v130, v35, v130
	v_fma_f32 v131, v36, v130, v131
	v_cvt_pk_bf16_f32 v132, v131, v131
	v_pk_fma_f32 v[74:75], v[2:3], v[130:131], v[114:115] op_sel_hi:[1,0,1]
	v_pk_fma_f32 v[78:79], v[4:5], v[130:131], v[116:117] op_sel_hi:[1,0,1]
	global_store_short v158, v132, s[100:101]
	v_pk_fma_f32 v[80:81], v[6:7], v[130:131], v[118:119] op_sel_hi:[1,0,1]
	v_pk_fma_f32 v[82:83], v[8:9], v[130:131], v[120:121] op_sel_hi:[1,0,1]
	v_pk_fma_f32 v[84:85], v[14:15], v[130:131], v[122:123] op_sel_hi:[1,0,1]
	v_pk_fma_f32 v[86:87], v[16:17], v[130:131], v[124:125] op_sel_hi:[1,0,1]
	v_pk_fma_f32 v[88:89], v[10:11], v[130:131], v[126:127] op_sel_hi:[1,0,1]
	v_pk_fma_f32 v[90:91], v[12:13], v[130:131], v[128:129] op_sel_hi:[1,0,1]
	s_waitcnt lgkmcnt(0)
	v_pk_mul_f32 v[114:115], v[70:71], v[74:75] op_sel_hi:[0,1]
	v_pk_mul_f32 v[116:117], v[70:71], v[78:79] op_sel_hi:[0,1]
	v_pk_fma_f32 v[110:111], v[114:115], v[50:51], 0 op_sel_hi:[1,1,0]
	v_pk_fma_f32 v[112:113], v[114:115], v[66:67], 0 op_sel_hi:[1,1,0]
	v_pk_mul_f32 v[118:119], v[70:71], v[80:81] op_sel_hi:[0,1]
	v_pk_fma_f32 v[110:111], v[116:117], v[52:53], v[110:111]
	v_pk_fma_f32 v[112:113], v[116:117], v[68:69], v[112:113]
	v_pk_mul_f32 v[120:121], v[70:71], v[82:83] op_sel_hi:[0,1]
	v_pk_fma_f32 v[110:111], v[118:119], v[46:47], v[110:111]
	v_pk_fma_f32 v[112:113], v[118:119], v[62:63], v[112:113]
	v_pk_mul_f32 v[122:123], v[70:71], v[84:85] op_sel_hi:[0,1]
	v_pk_fma_f32 v[110:111], v[120:121], v[48:49], v[110:111]
	v_pk_fma_f32 v[112:113], v[120:121], v[64:65], v[112:113]
	v_pk_mul_f32 v[124:125], v[70:71], v[86:87] op_sel_hi:[0,1]
	v_pk_fma_f32 v[110:111], v[122:123], v[42:43], v[110:111]
	v_pk_fma_f32 v[112:113], v[122:123], v[58:59], v[112:113]
	v_pk_mul_f32 v[126:127], v[70:71], v[88:89] op_sel_hi:[0,1]
	v_pk_fma_f32 v[110:111], v[124:125], v[44:45], v[110:111]
	v_pk_fma_f32 v[112:113], v[124:125], v[60:61], v[112:113]
	v_pk_mul_f32 v[128:129], v[70:71], v[90:91] op_sel_hi:[0,1]
	v_pk_fma_f32 v[110:111], v[126:127], v[38:39], v[110:111]
	v_pk_fma_f32 v[112:113], v[126:127], v[54:55], v[112:113]
	v_pk_fma_f32 v[110:111], v[128:129], v[40:41], v[110:111]
	v_pk_fma_f32 v[112:113], v[128:129], v[56:57], v[112:113]
	v_add_f32_e32 v134, v110, v111
	v_add_f32_e32 v135, v112, v113
	s_nop 0
	v_add_f32_dpp v134, v134, v134 quad_perm:[1,0,3,2] row_mask:0xf bank_mask:0xf bound_ctrl:1
	v_add_f32_dpp v135, v135, v135 quad_perm:[1,0,3,2] row_mask:0xf bank_mask:0xf bound_ctrl:1
	s_nop 0
	v_add_f32_dpp v134, v134, v134 quad_perm:[2,3,0,1] row_mask:0xf bank_mask:0xf bound_ctrl:1
	v_add_f32_dpp v135, v135, v135 quad_perm:[2,3,0,1] row_mask:0xf bank_mask:0xf bound_ctrl:1
	v_sub_f32_e32 v134, v0, v134
	v_mul_f32_e32 v134, v71, v134
	v_fma_f32 v135, v72, v134, v135
	v_cvt_pk_bf16_f32 v133, v135, v135
	v_pk_fma_f32 v[74:75], v[50:51], v[134:135], v[114:115] op_sel_hi:[1,0,1]
	v_pk_fma_f32 v[78:79], v[52:53], v[134:135], v[116:117] op_sel_hi:[1,0,1]
	global_store_short v159, v133, s[100:101]
	v_pk_fma_f32 v[80:81], v[46:47], v[134:135], v[118:119] op_sel_hi:[1,0,1]
	v_pk_fma_f32 v[82:83], v[48:49], v[134:135], v[120:121] op_sel_hi:[1,0,1]
	v_pk_fma_f32 v[84:85], v[42:43], v[134:135], v[122:123] op_sel_hi:[1,0,1]
	v_pk_fma_f32 v[86:87], v[44:45], v[134:135], v[124:125] op_sel_hi:[1,0,1]
	v_pk_fma_f32 v[88:89], v[38:39], v[134:135], v[126:127] op_sel_hi:[1,0,1]
	v_pk_fma_f32 v[90:91], v[40:41], v[134:135], v[128:129] op_sel_hi:[1,0,1]

.LBB0_916:
	v_readfirstlane_b32 s100, v92
	v_readfirstlane_b32 s101, v93
	s_sub_u32 s100, s100, m0
	s_subb_u32 s101, s101, 0
	s_waitcnt lgkmcnt(0)
	v_pk_mul_f32 v[114:115], v[34:35], v[74:75] op_sel_hi:[0,1]
	v_pk_mul_f32 v[116:117], v[34:35], v[78:79] op_sel_hi:[0,1]
	v_pk_fma_f32 v[106:107], v[114:115], v[2:3], 0 op_sel_hi:[1,1,0]
	v_pk_fma_f32 v[108:109], v[114:115], v[30:31], 0 op_sel_hi:[1,1,0]
	v_pk_mul_f32 v[118:119], v[34:35], v[80:81] op_sel_hi:[0,1]
	ds_read_b128 v[66:69], v94 offset:13600
	v_pk_fma_f32 v[106:107], v[116:117], v[4:5], v[106:107]
	v_pk_fma_f32 v[108:109], v[116:117], v[32:33], v[108:109]
	v_pk_mul_f32 v[120:121], v[34:35], v[82:83] op_sel_hi:[0,1]
	ds_read_b128 v[62:65], v94 offset:13616
	v_pk_fma_f32 v[106:107], v[118:119], v[6:7], v[106:107]
	v_pk_fma_f32 v[108:109], v[118:119], v[26:27], v[108:109]
	v_pk_mul_f32 v[122:123], v[34:35], v[84:85] op_sel_hi:[0,1]
	ds_read_b128 v[58:61], v94 offset:13632
	v_pk_fma_f32 v[106:107], v[120:121], v[8:9], v[106:107]
	v_pk_fma_f32 v[108:109], v[120:121], v[28:29], v[108:109]
	v_pk_mul_f32 v[124:125], v[34:35], v[86:87] op_sel_hi:[0,1]
	ds_read_b128 v[54:57], v94 offset:13648
	v_pk_fma_f32 v[106:107], v[122:123], v[14:15], v[106:107]
	v_pk_fma_f32 v[108:109], v[122:123], v[22:23], v[108:109]
	v_pk_mul_f32 v[126:127], v[34:35], v[88:89] op_sel_hi:[0,1]
	ds_read_b128 v[50:53], v94 offset:13856
	v_pk_fma_f32 v[106:107], v[124:125], v[16:17], v[106:107]
	v_pk_fma_f32 v[108:109], v[124:125], v[24:25], v[108:109]
	v_pk_mul_f32 v[128:129], v[34:35], v[90:91] op_sel_hi:[0,1]
	ds_read_b128 v[46:49], v94 offset:13872
	v_pk_fma_f32 v[106:107], v[126:127], v[10:11], v[106:107]
	v_pk_fma_f32 v[108:109], v[126:127], v[18:19], v[108:109]
	ds_read_b128 v[42:45], v94 offset:13888
	v_pk_fma_f32 v[106:107], v[128:129], v[12:13], v[106:107]
	v_pk_fma_f32 v[108:109], v[128:129], v[20:21], v[108:109]
	ds_read_b128 v[38:41], v94 offset:13904
	v_add_f32_e32 v130, v106, v107
	v_add_f32_e32 v131, v108, v109
	ds_read_b32 v0, v95 offset:14112
	v_add_f32_dpp v130, v130, v130 quad_perm:[1,0,3,2] row_mask:0xf bank_mask:0xf bound_ctrl:1
	v_add_f32_dpp v131, v131, v131 quad_perm:[1,0,3,2] row_mask:0xf bank_mask:0xf bound_ctrl:1
	ds_read_b96 v[70:72], v1 offset:14368
	v_add_f32_dpp v130, v130, v130 quad_perm:[2,3,0,1] row_mask:0xf bank_mask:0xf bound_ctrl:1
	v_add_f32_dpp v131, v131, v131 quad_perm:[2,3,0,1] row_mask:0xf bank_mask:0xf bound_ctrl:1
	v_sub_f32_e32 v130, v73, v130
	v_mul_f32_e32 v130, v35, v130
	v_fma_f32 v131, v36, v130, v131
	v_cvt_pk_bf16_f32 v132, v131, v131
	v_pk_fma_f32 v[74:75], v[2:3], v[130:131], v[114:115] op_sel_hi:[1,0,1]
	v_pk_fma_f32 v[78:79], v[4:5], v[130:131], v[116:117] op_sel_hi:[1,0,1]
	global_store_short v144, v132, s[100:101]
	v_pk_fma_f32 v[80:81], v[6:7], v[130:131], v[118:119] op_sel_hi:[1,0,1]
	v_pk_fma_f32 v[82:83], v[8:9], v[130:131], v[120:121] op_sel_hi:[1,0,1]
	v_pk_fma_f32 v[84:85], v[14:15], v[130:131], v[122:123] op_sel_hi:[1,0,1]
	v_pk_fma_f32 v[86:87], v[16:17], v[130:131], v[124:125] op_sel_hi:[1,0,1]
	v_pk_fma_f32 v[88:89], v[10:11], v[130:131], v[126:127] op_sel_hi:[1,0,1]
	v_pk_fma_f32 v[90:91], v[12:13], v[130:131], v[128:129] op_sel_hi:[1,0,1]
	s_waitcnt lgkmcnt(0)
	v_pk_mul_f32 v[114:115], v[70:71], v[74:75] op_sel_hi:[0,1]
	v_pk_mul_f32 v[116:117], v[70:71], v[78:79] op_sel_hi:[0,1]
	v_pk_fma_f32 v[110:111], v[114:115], v[50:51], 0 op_sel_hi:[1,1,0]
	v_pk_fma_f32 v[112:113], v[114:115], v[66:67], 0 op_sel_hi:[1,1,0]
	v_pk_mul_f32 v[118:119], v[70:71], v[80:81] op_sel_hi:[0,1]
	ds_read_b128 v[30:33], v94 offset:14400
	v_pk_fma_f32 v[110:111], v[116:117], v[52:53], v[110:111]
	v_pk_fma_f32 v[112:113], v[116:117], v[68:69], v[112:113]
	v_pk_mul_f32 v[120:121], v[70:71], v[82:83] op_sel_hi:[0,1]
	ds_read_b128 v[26:29], v94 offset:14416
	v_pk_fma_f32 v[110:111], v[118:119], v[46:47], v[110:111]
	v_pk_fma_f32 v[112:113], v[118:119], v[62:63], v[112:113]
	v_pk_mul_f32 v[122:123], v[70:71], v[84:85] op_sel_hi:[0,1]
	ds_read_b128 v[22:25], v94 offset:14432
	v_pk_fma_f32 v[110:111], v[120:121], v[48:49], v[110:111]
	v_pk_fma_f32 v[112:113], v[120:121], v[64:65], v[112:113]
	v_pk_mul_f32 v[124:125], v[70:71], v[86:87] op_sel_hi:[0,1]
	ds_read_b128 v[18:21], v94 offset:14448
	v_pk_fma_f32 v[110:111], v[122:123], v[42:43], v[110:111]
	v_pk_fma_f32 v[112:113], v[122:123], v[58:59], v[112:113]
	v_pk_mul_f32 v[126:127], v[70:71], v[88:89] op_sel_hi:[0,1]
	ds_read_b128 v[2:5], v94 offset:14656
	v_pk_fma_f32 v[110:111], v[124:125], v[44:45], v[110:111]
	v_pk_fma_f32 v[112:113], v[124:125], v[60:61], v[112:113]
	v_pk_mul_f32 v[128:129], v[70:71], v[90:91] op_sel_hi:[0,1]
	ds_read_b128 v[6:9], v94 offset:14672
	v_pk_fma_f32 v[110:111], v[126:127], v[38:39], v[110:111]
	v_pk_fma_f32 v[112:113], v[126:127], v[54:55], v[112:113]
	ds_read_b128 v[14:17], v94 offset:14688
	v_pk_fma_f32 v[110:111], v[128:129], v[40:41], v[110:111]
	v_pk_fma_f32 v[112:113], v[128:129], v[56:57], v[112:113]
	ds_read_b128 v[10:13], v94 offset:14704
	v_add_f32_e32 v134, v110, v111
	v_add_f32_e32 v135, v112, v113
	ds_read_b32 v73, v95 offset:14912
	v_add_f32_dpp v134, v134, v134 quad_perm:[1,0,3,2] row_mask:0xf bank_mask:0xf bound_ctrl:1
	v_add_f32_dpp v135, v135, v135 quad_perm:[1,0,3,2] row_mask:0xf bank_mask:0xf bound_ctrl:1
	ds_read_b96 v[34:36], v1 offset:15168
	v_add_f32_dpp v134, v134, v134 quad_perm:[2,3,0,1] row_mask:0xf bank_mask:0xf bound_ctrl:1
	v_add_f32_dpp v135, v135, v135 quad_perm:[2,3,0,1] row_mask:0xf bank_mask:0xf bound_ctrl:1
	v_sub_f32_e32 v134, v0, v134
	v_mul_f32_e32 v134, v71, v134
	v_fma_f32 v135, v72, v134, v135
	v_cvt_pk_bf16_f32 v133, v135, v135
	v_pk_fma_f32 v[74:75], v[50:51], v[134:135], v[114:115] op_sel_hi:[1,0,1]
	v_pk_fma_f32 v[78:79], v[52:53], v[134:135], v[116:117] op_sel_hi:[1,0,1]
	global_store_short v145, v133, s[100:101]
	v_pk_fma_f32 v[80:81], v[46:47], v[134:135], v[118:119] op_sel_hi:[1,0,1]
	v_pk_fma_f32 v[82:83], v[48:49], v[134:135], v[120:121] op_sel_hi:[1,0,1]
	v_pk_fma_f32 v[84:85], v[42:43], v[134:135], v[122:123] op_sel_hi:[1,0,1]
	v_pk_fma_f32 v[86:87], v[44:45], v[134:135], v[124:125] op_sel_hi:[1,0,1]
	v_pk_fma_f32 v[88:89], v[38:39], v[134:135], v[126:127] op_sel_hi:[1,0,1]
	v_pk_fma_f32 v[90:91], v[40:41], v[134:135], v[128:129] op_sel_hi:[1,0,1]
	s_waitcnt lgkmcnt(0)
	v_pk_mul_f32 v[114:115], v[34:35], v[74:75] op_sel_hi:[0,1]
	v_pk_mul_f32 v[116:117], v[34:35], v[78:79] op_sel_hi:[0,1]
	v_pk_fma_f32 v[106:107], v[114:115], v[2:3], 0 op_sel_hi:[1,1,0]
	v_pk_fma_f32 v[108:109], v[114:115], v[30:31], 0 op_sel_hi:[1,1,0]
	v_pk_mul_f32 v[118:119], v[34:35], v[80:81] op_sel_hi:[0,1]
	ds_read_b128 v[66:69], v94 offset:15200
	v_pk_fma_f32 v[106:107], v[116:117], v[4:5], v[106:107]
	v_pk_fma_f32 v[108:109], v[116:117], v[32:33], v[108:109]
	v_pk_mul_f32 v[120:121], v[34:35], v[82:83] op_sel_hi:[0,1]
	ds_read_b128 v[62:65], v94 offset:15216
	v_pk_fma_f32 v[106:107], v[118:119], v[6:7], v[106:107]
	v_pk_fma_f32 v[108:109], v[118:119], v[26:27], v[108:109]
	v_pk_mul_f32 v[122:123], v[34:35], v[84:85] op_sel_hi:[0,1]
	ds_read_b128 v[58:61], v94 offset:15232
	v_pk_fma_f32 v[106:107], v[120:121], v[8:9], v[106:107]
	v_pk_fma_f32 v[108:109], v[120:121], v[28:29], v[108:109]
	v_pk_mul_f32 v[124:125], v[34:35], v[86:87] op_sel_hi:[0,1]
	ds_read_b128 v[54:57], v94 offset:15248
	v_pk_fma_f32 v[106:107], v[122:123], v[14:15], v[106:107]
	v_pk_fma_f32 v[108:109], v[122:123], v[22:23], v[108:109]
	v_pk_mul_f32 v[126:127], v[34:35], v[88:89] op_sel_hi:[0,1]
	ds_read_b128 v[50:53], v94 offset:15456
	v_pk_fma_f32 v[106:107], v[124:125], v[16:17], v[106:107]
	v_pk_fma_f32 v[108:109], v[124:125], v[24:25], v[108:109]
	v_pk_mul_f32 v[128:129], v[34:35], v[90:91] op_sel_hi:[0,1]
	ds_read_b128 v[46:49], v94 offset:15472
	v_pk_fma_f32 v[106:107], v[126:127], v[10:11], v[106:107]
	v_pk_fma_f32 v[108:109], v[126:127], v[18:19], v[108:109]
	ds_read_b128 v[42:45], v94 offset:15488
	v_pk_fma_f32 v[106:107], v[128:129], v[12:13], v[106:107]
	v_pk_fma_f32 v[108:109], v[128:129], v[20:21], v[108:109]
	ds_read_b128 v[38:41], v94 offset:15504
	v_add_f32_e32 v130, v106, v107
	v_add_f32_e32 v131, v108, v109
	ds_read_b32 v0, v95 offset:15712
	v_add_f32_dpp v130, v130, v130 quad_perm:[1,0,3,2] row_mask:0xf bank_mask:0xf bound_ctrl:1
	v_add_f32_dpp v131, v131, v131 quad_perm:[1,0,3,2] row_mask:0xf bank_mask:0xf bound_ctrl:1
	ds_read_b96 v[70:72], v1 offset:15968
	v_add_f32_dpp v130, v130, v130 quad_perm:[2,3,0,1] row_mask:0xf bank_mask:0xf bound_ctrl:1
	v_add_f32_dpp v131, v131, v131 quad_perm:[2,3,0,1] row_mask:0xf bank_mask:0xf bound_ctrl:1
	v_sub_f32_e32 v130, v73, v130
	v_mul_f32_e32 v130, v35, v130
	v_fma_f32 v131, v36, v130, v131
	v_cvt_pk_bf16_f32 v132, v131, v131
	v_pk_fma_f32 v[74:75], v[2:3], v[130:131], v[114:115] op_sel_hi:[1,0,1]
	v_pk_fma_f32 v[78:79], v[4:5], v[130:131], v[116:117] op_sel_hi:[1,0,1]
	global_store_short v146, v132, s[100:101]
	v_pk_fma_f32 v[80:81], v[6:7], v[130:131], v[118:119] op_sel_hi:[1,0,1]
	v_pk_fma_f32 v[82:83], v[8:9], v[130:131], v[120:121] op_sel_hi:[1,0,1]
	v_pk_fma_f32 v[84:85], v[14:15], v[130:131], v[122:123] op_sel_hi:[1,0,1]
	v_pk_fma_f32 v[86:87], v[16:17], v[130:131], v[124:125] op_sel_hi:[1,0,1]
	v_pk_fma_f32 v[88:89], v[10:11], v[130:131], v[126:127] op_sel_hi:[1,0,1]
	v_pk_fma_f32 v[90:91], v[12:13], v[130:131], v[128:129] op_sel_hi:[1,0,1]
	s_waitcnt lgkmcnt(0)
	v_pk_mul_f32 v[114:115], v[70:71], v[74:75] op_sel_hi:[0,1]
	v_pk_mul_f32 v[116:117], v[70:71], v[78:79] op_sel_hi:[0,1]
	v_pk_fma_f32 v[110:111], v[114:115], v[50:51], 0 op_sel_hi:[1,1,0]
	v_pk_fma_f32 v[112:113], v[114:115], v[66:67], 0 op_sel_hi:[1,1,0]
	v_pk_mul_f32 v[118:119], v[70:71], v[80:81] op_sel_hi:[0,1]
	ds_read_b128 v[30:33], v94 offset:16000
	v_pk_fma_f32 v[110:111], v[116:117], v[52:53], v[110:111]
	v_pk_fma_f32 v[112:113], v[116:117], v[68:69], v[112:113]
	v_pk_mul_f32 v[120:121], v[70:71], v[82:83] op_sel_hi:[0,1]
	ds_read_b128 v[26:29], v94 offset:16016
	v_pk_fma_f32 v[110:111], v[118:119], v[46:47], v[110:111]
	v_pk_fma_f32 v[112:113], v[118:119], v[62:63], v[112:113]
	v_pk_mul_f32 v[122:123], v[70:71], v[84:85] op_sel_hi:[0,1]
	ds_read_b128 v[22:25], v94 offset:16032
	v_pk_fma_f32 v[110:111], v[120:121], v[48:49], v[110:111]
	v_pk_fma_f32 v[112:113], v[120:121], v[64:65], v[112:113]
	v_pk_mul_f32 v[124:125], v[70:71], v[86:87] op_sel_hi:[0,1]
	ds_read_b128 v[18:21], v94 offset:16048
	v_pk_fma_f32 v[110:111], v[122:123], v[42:43], v[110:111]
	v_pk_fma_f32 v[112:113], v[122:123], v[58:59], v[112:113]
	v_pk_mul_f32 v[126:127], v[70:71], v[88:89] op_sel_hi:[0,1]
	ds_read_b128 v[2:5], v94 offset:16256
	v_pk_fma_f32 v[110:111], v[124:125], v[44:45], v[110:111]
	v_pk_fma_f32 v[112:113], v[124:125], v[60:61], v[112:113]
	v_pk_mul_f32 v[128:129], v[70:71], v[90:91] op_sel_hi:[0,1]
	ds_read_b128 v[6:9], v94 offset:16272
	v_pk_fma_f32 v[110:111], v[126:127], v[38:39], v[110:111]
	v_pk_fma_f32 v[112:113], v[126:127], v[54:55], v[112:113]
	ds_read_b128 v[14:17], v94 offset:16288
	v_pk_fma_f32 v[110:111], v[128:129], v[40:41], v[110:111]
	v_pk_fma_f32 v[112:113], v[128:129], v[56:57], v[112:113]
	ds_read_b128 v[10:13], v94 offset:16304
	v_add_f32_e32 v134, v110, v111
	v_add_f32_e32 v135, v112, v113
	ds_read_b32 v73, v95 offset:16512
	v_add_f32_dpp v134, v134, v134 quad_perm:[1,0,3,2] row_mask:0xf bank_mask:0xf bound_ctrl:1
	v_add_f32_dpp v135, v135, v135 quad_perm:[1,0,3,2] row_mask:0xf bank_mask:0xf bound_ctrl:1
	ds_read_b96 v[34:36], v1 offset:16768
	v_add_f32_dpp v134, v134, v134 quad_perm:[2,3,0,1] row_mask:0xf bank_mask:0xf bound_ctrl:1
	v_add_f32_dpp v135, v135, v135 quad_perm:[2,3,0,1] row_mask:0xf bank_mask:0xf bound_ctrl:1
	v_sub_f32_e32 v134, v0, v134
	v_mul_f32_e32 v134, v71, v134
	v_fma_f32 v135, v72, v134, v135
	v_cvt_pk_bf16_f32 v133, v135, v135
	v_pk_fma_f32 v[74:75], v[50:51], v[134:135], v[114:115] op_sel_hi:[1,0,1]
	v_pk_fma_f32 v[78:79], v[52:53], v[134:135], v[116:117] op_sel_hi:[1,0,1]
	global_store_short v147, v133, s[100:101]
	v_pk_fma_f32 v[80:81], v[46:47], v[134:135], v[118:119] op_sel_hi:[1,0,1]
	v_pk_fma_f32 v[82:83], v[48:49], v[134:135], v[120:121] op_sel_hi:[1,0,1]
	v_pk_fma_f32 v[84:85], v[42:43], v[134:135], v[122:123] op_sel_hi:[1,0,1]
	v_pk_fma_f32 v[86:87], v[44:45], v[134:135], v[124:125] op_sel_hi:[1,0,1]
	v_pk_fma_f32 v[88:89], v[38:39], v[134:135], v[126:127] op_sel_hi:[1,0,1]
	v_pk_fma_f32 v[90:91], v[40:41], v[134:135], v[128:129] op_sel_hi:[1,0,1]
	s_waitcnt lgkmcnt(0)
	v_pk_mul_f32 v[114:115], v[34:35], v[74:75] op_sel_hi:[0,1]
	v_pk_mul_f32 v[116:117], v[34:35], v[78:79] op_sel_hi:[0,1]
	v_pk_fma_f32 v[106:107], v[114:115], v[2:3], 0 op_sel_hi:[1,1,0]
	v_pk_fma_f32 v[108:109], v[114:115], v[30:31], 0 op_sel_hi:[1,1,0]
	v_pk_mul_f32 v[118:119], v[34:35], v[80:81] op_sel_hi:[0,1]
	ds_read_b128 v[66:69], v94 offset:16800
	v_pk_fma_f32 v[106:107], v[116:117], v[4:5], v[106:107]
	v_pk_fma_f32 v[108:109], v[116:117], v[32:33], v[108:109]
	v_pk_mul_f32 v[120:121], v[34:35], v[82:83] op_sel_hi:[0,1]
	ds_read_b128 v[62:65], v94 offset:16816
	v_pk_fma_f32 v[106:107], v[118:119], v[6:7], v[106:107]
	v_pk_fma_f32 v[108:109], v[118:119], v[26:27], v[108:109]
	v_pk_mul_f32 v[122:123], v[34:35], v[84:85] op_sel_hi:[0,1]
	ds_read_b128 v[58:61], v94 offset:16832
	v_pk_fma_f32 v[106:107], v[120:121], v[8:9], v[106:107]
	v_pk_fma_f32 v[108:109], v[120:121], v[28:29], v[108:109]
	v_pk_mul_f32 v[124:125], v[34:35], v[86:87] op_sel_hi:[0,1]
	ds_read_b128 v[54:57], v94 offset:16848
	v_pk_fma_f32 v[106:107], v[122:123], v[14:15], v[106:107]
	v_pk_fma_f32 v[108:109], v[122:123], v[22:23], v[108:109]
	v_pk_mul_f32 v[126:127], v[34:35], v[88:89] op_sel_hi:[0,1]
	ds_read_b128 v[50:53], v94 offset:17056
	v_pk_fma_f32 v[106:107], v[124:125], v[16:17], v[106:107]
	v_pk_fma_f32 v[108:109], v[124:125], v[24:25], v[108:109]
	v_pk_mul_f32 v[128:129], v[34:35], v[90:91] op_sel_hi:[0,1]
	ds_read_b128 v[46:49], v94 offset:17072
	v_pk_fma_f32 v[106:107], v[126:127], v[10:11], v[106:107]
	v_pk_fma_f32 v[108:109], v[126:127], v[18:19], v[108:109]
	ds_read_b128 v[42:45], v94 offset:17088
	v_pk_fma_f32 v[106:107], v[128:129], v[12:13], v[106:107]
	v_pk_fma_f32 v[108:109], v[128:129], v[20:21], v[108:109]
	ds_read_b128 v[38:41], v94 offset:17104
	v_add_f32_e32 v130, v106, v107
	v_add_f32_e32 v131, v108, v109
	ds_read_b32 v0, v95 offset:17312
	v_add_f32_dpp v130, v130, v130 quad_perm:[1,0,3,2] row_mask:0xf bank_mask:0xf bound_ctrl:1
	v_add_f32_dpp v131, v131, v131 quad_perm:[1,0,3,2] row_mask:0xf bank_mask:0xf bound_ctrl:1
	ds_read_b96 v[70:72], v1 offset:17568
	v_add_f32_dpp v130, v130, v130 quad_perm:[2,3,0,1] row_mask:0xf bank_mask:0xf bound_ctrl:1
	v_add_f32_dpp v131, v131, v131 quad_perm:[2,3,0,1] row_mask:0xf bank_mask:0xf bound_ctrl:1
	v_sub_f32_e32 v130, v73, v130
	v_mul_f32_e32 v130, v35, v130
	v_fma_f32 v131, v36, v130, v131
	v_cvt_pk_bf16_f32 v132, v131, v131
	v_pk_fma_f32 v[74:75], v[2:3], v[130:131], v[114:115] op_sel_hi:[1,0,1]
	v_pk_fma_f32 v[78:79], v[4:5], v[130:131], v[116:117] op_sel_hi:[1,0,1]
	global_store_short v148, v132, s[100:101]
	v_pk_fma_f32 v[80:81], v[6:7], v[130:131], v[118:119] op_sel_hi:[1,0,1]
	v_pk_fma_f32 v[82:83], v[8:9], v[130:131], v[120:121] op_sel_hi:[1,0,1]
	v_pk_fma_f32 v[84:85], v[14:15], v[130:131], v[122:123] op_sel_hi:[1,0,1]
	v_pk_fma_f32 v[86:87], v[16:17], v[130:131], v[124:125] op_sel_hi:[1,0,1]
	v_pk_fma_f32 v[88:89], v[10:11], v[130:131], v[126:127] op_sel_hi:[1,0,1]
	v_pk_fma_f32 v[90:91], v[12:13], v[130:131], v[128:129] op_sel_hi:[1,0,1]
	s_waitcnt lgkmcnt(0)
	v_pk_mul_f32 v[114:115], v[70:71], v[74:75] op_sel_hi:[0,1]
	v_pk_mul_f32 v[116:117], v[70:71], v[78:79] op_sel_hi:[0,1]
	v_pk_fma_f32 v[110:111], v[114:115], v[50:51], 0 op_sel_hi:[1,1,0]
	v_pk_fma_f32 v[112:113], v[114:115], v[66:67], 0 op_sel_hi:[1,1,0]
	v_pk_mul_f32 v[118:119], v[70:71], v[80:81] op_sel_hi:[0,1]
	ds_read_b128 v[30:33], v94 offset:17600
	v_pk_fma_f32 v[110:111], v[116:117], v[52:53], v[110:111]
	v_pk_fma_f32 v[112:113], v[116:117], v[68:69], v[112:113]
	v_pk_mul_f32 v[120:121], v[70:71], v[82:83] op_sel_hi:[0,1]
	ds_read_b128 v[26:29], v94 offset:17616
	v_pk_fma_f32 v[110:111], v[118:119], v[46:47], v[110:111]
	v_pk_fma_f32 v[112:113], v[118:119], v[62:63], v[112:113]
	v_pk_mul_f32 v[122:123], v[70:71], v[84:85] op_sel_hi:[0,1]
	ds_read_b128 v[22:25], v94 offset:17632
	v_pk_fma_f32 v[110:111], v[120:121], v[48:49], v[110:111]
	v_pk_fma_f32 v[112:113], v[120:121], v[64:65], v[112:113]
	v_pk_mul_f32 v[124:125], v[70:71], v[86:87] op_sel_hi:[0,1]
	ds_read_b128 v[18:21], v94 offset:17648
	v_pk_fma_f32 v[110:111], v[122:123], v[42:43], v[110:111]
	v_pk_fma_f32 v[112:113], v[122:123], v[58:59], v[112:113]
	v_pk_mul_f32 v[126:127], v[70:71], v[88:89] op_sel_hi:[0,1]
	ds_read_b128 v[2:5], v94 offset:17856
	v_pk_fma_f32 v[110:111], v[124:125], v[44:45], v[110:111]
	v_pk_fma_f32 v[112:113], v[124:125], v[60:61], v[112:113]
	v_pk_mul_f32 v[128:129], v[70:71], v[90:91] op_sel_hi:[0,1]
	ds_read_b128 v[6:9], v94 offset:17872
	v_pk_fma_f32 v[110:111], v[126:127], v[38:39], v[110:111]
	v_pk_fma_f32 v[112:113], v[126:127], v[54:55], v[112:113]
	ds_read_b128 v[14:17], v94 offset:17888
	v_pk_fma_f32 v[110:111], v[128:129], v[40:41], v[110:111]
	v_pk_fma_f32 v[112:113], v[128:129], v[56:57], v[112:113]
	ds_read_b128 v[10:13], v94 offset:17904
	v_add_f32_e32 v134, v110, v111
	v_add_f32_e32 v135, v112, v113
	ds_read_b32 v73, v95 offset:18112
	v_add_f32_dpp v134, v134, v134 quad_perm:[1,0,3,2] row_mask:0xf bank_mask:0xf bound_ctrl:1
	v_add_f32_dpp v135, v135, v135 quad_perm:[1,0,3,2] row_mask:0xf bank_mask:0xf bound_ctrl:1
	ds_read_b96 v[34:36], v1 offset:18368
	v_add_f32_dpp v134, v134, v134 quad_perm:[2,3,0,1] row_mask:0xf bank_mask:0xf bound_ctrl:1
	v_add_f32_dpp v135, v135, v135 quad_perm:[2,3,0,1] row_mask:0xf bank_mask:0xf bound_ctrl:1
	v_sub_f32_e32 v134, v0, v134
	v_mul_f32_e32 v134, v71, v134
	v_fma_f32 v135, v72, v134, v135
	v_cvt_pk_bf16_f32 v133, v135, v135
	v_pk_fma_f32 v[74:75], v[50:51], v[134:135], v[114:115] op_sel_hi:[1,0,1]
	v_pk_fma_f32 v[78:79], v[52:53], v[134:135], v[116:117] op_sel_hi:[1,0,1]
	global_store_short v149, v133, s[100:101]
	v_pk_fma_f32 v[80:81], v[46:47], v[134:135], v[118:119] op_sel_hi:[1,0,1]
	v_pk_fma_f32 v[82:83], v[48:49], v[134:135], v[120:121] op_sel_hi:[1,0,1]
	v_pk_fma_f32 v[84:85], v[42:43], v[134:135], v[122:123] op_sel_hi:[1,0,1]
	v_pk_fma_f32 v[86:87], v[44:45], v[134:135], v[124:125] op_sel_hi:[1,0,1]
	v_pk_fma_f32 v[88:89], v[38:39], v[134:135], v[126:127] op_sel_hi:[1,0,1]
	v_pk_fma_f32 v[90:91], v[40:41], v[134:135], v[128:129] op_sel_hi:[1,0,1]
	s_waitcnt lgkmcnt(0)
	v_pk_mul_f32 v[114:115], v[34:35], v[74:75] op_sel_hi:[0,1]
	v_pk_mul_f32 v[116:117], v[34:35], v[78:79] op_sel_hi:[0,1]
	v_pk_fma_f32 v[106:107], v[114:115], v[2:3], 0 op_sel_hi:[1,1,0]
	v_pk_fma_f32 v[108:109], v[114:115], v[30:31], 0 op_sel_hi:[1,1,0]
	v_pk_mul_f32 v[118:119], v[34:35], v[80:81] op_sel_hi:[0,1]
	ds_read_b128 v[66:69], v94 offset:18400
	v_pk_fma_f32 v[106:107], v[116:117], v[4:5], v[106:107]
	v_pk_fma_f32 v[108:109], v[116:117], v[32:33], v[108:109]
	v_pk_mul_f32 v[120:121], v[34:35], v[82:83] op_sel_hi:[0,1]
	ds_read_b128 v[62:65], v94 offset:18416
	v_pk_fma_f32 v[106:107], v[118:119], v[6:7], v[106:107]
	v_pk_fma_f32 v[108:109], v[118:119], v[26:27], v[108:109]
	v_pk_mul_f32 v[122:123], v[34:35], v[84:85] op_sel_hi:[0,1]
	ds_read_b128 v[58:61], v94 offset:18432
	v_pk_fma_f32 v[106:107], v[120:121], v[8:9], v[106:107]
	v_pk_fma_f32 v[108:109], v[120:121], v[28:29], v[108:109]
	v_pk_mul_f32 v[124:125], v[34:35], v[86:87] op_sel_hi:[0,1]
	ds_read_b128 v[54:57], v94 offset:18448
	v_pk_fma_f32 v[106:107], v[122:123], v[14:15], v[106:107]
	v_pk_fma_f32 v[108:109], v[122:123], v[22:23], v[108:109]
	v_pk_mul_f32 v[126:127], v[34:35], v[88:89] op_sel_hi:[0,1]
	ds_read_b128 v[50:53], v94 offset:18656
	v_pk_fma_f32 v[106:107], v[124:125], v[16:17], v[106:107]
	v_pk_fma_f32 v[108:109], v[124:125], v[24:25], v[108:109]
	v_pk_mul_f32 v[128:129], v[34:35], v[90:91] op_sel_hi:[0,1]
	ds_read_b128 v[46:49], v94 offset:18672
	v_pk_fma_f32 v[106:107], v[126:127], v[10:11], v[106:107]
	v_pk_fma_f32 v[108:109], v[126:127], v[18:19], v[108:109]
	ds_read_b128 v[42:45], v94 offset:18688
	v_pk_fma_f32 v[106:107], v[128:129], v[12:13], v[106:107]
	v_pk_fma_f32 v[108:109], v[128:129], v[20:21], v[108:109]
	ds_read_b128 v[38:41], v94 offset:18704
	v_add_f32_e32 v130, v106, v107
	v_add_f32_e32 v131, v108, v109
	ds_read_b32 v0, v95 offset:18912
	v_add_f32_dpp v130, v130, v130 quad_perm:[1,0,3,2] row_mask:0xf bank_mask:0xf bound_ctrl:1
	v_add_f32_dpp v131, v131, v131 quad_perm:[1,0,3,2] row_mask:0xf bank_mask:0xf bound_ctrl:1
	ds_read_b96 v[70:72], v1 offset:19168
	v_add_f32_dpp v130, v130, v130 quad_perm:[2,3,0,1] row_mask:0xf bank_mask:0xf bound_ctrl:1
	v_add_f32_dpp v131, v131, v131 quad_perm:[2,3,0,1] row_mask:0xf bank_mask:0xf bound_ctrl:1
	v_sub_f32_e32 v130, v73, v130
	v_mul_f32_e32 v130, v35, v130
	v_fma_f32 v131, v36, v130, v131
	v_cvt_pk_bf16_f32 v132, v131, v131
	v_pk_fma_f32 v[74:75], v[2:3], v[130:131], v[114:115] op_sel_hi:[1,0,1]
	v_pk_fma_f32 v[78:79], v[4:5], v[130:131], v[116:117] op_sel_hi:[1,0,1]
	global_store_short v150, v132, s[100:101]
	v_pk_fma_f32 v[80:81], v[6:7], v[130:131], v[118:119] op_sel_hi:[1,0,1]
	v_pk_fma_f32 v[82:83], v[8:9], v[130:131], v[120:121] op_sel_hi:[1,0,1]
	v_pk_fma_f32 v[84:85], v[14:15], v[130:131], v[122:123] op_sel_hi:[1,0,1]
	v_pk_fma_f32 v[86:87], v[16:17], v[130:131], v[124:125] op_sel_hi:[1,0,1]
	v_pk_fma_f32 v[88:89], v[10:11], v[130:131], v[126:127] op_sel_hi:[1,0,1]
	v_pk_fma_f32 v[90:91], v[12:13], v[130:131], v[128:129] op_sel_hi:[1,0,1]
	s_waitcnt lgkmcnt(0)
	v_pk_mul_f32 v[114:115], v[70:71], v[74:75] op_sel_hi:[0,1]
	v_pk_mul_f32 v[116:117], v[70:71], v[78:79] op_sel_hi:[0,1]
	v_pk_fma_f32 v[110:111], v[114:115], v[50:51], 0 op_sel_hi:[1,1,0]
	v_pk_fma_f32 v[112:113], v[114:115], v[66:67], 0 op_sel_hi:[1,1,0]
	v_pk_mul_f32 v[118:119], v[70:71], v[80:81] op_sel_hi:[0,1]
	ds_read_b128 v[30:33], v94 offset:19200
	v_pk_fma_f32 v[110:111], v[116:117], v[52:53], v[110:111]
	v_pk_fma_f32 v[112:113], v[116:117], v[68:69], v[112:113]
	v_pk_mul_f32 v[120:121], v[70:71], v[82:83] op_sel_hi:[0,1]
	ds_read_b128 v[26:29], v94 offset:19216
	v_pk_fma_f32 v[110:111], v[118:119], v[46:47], v[110:111]
	v_pk_fma_f32 v[112:113], v[118:119], v[62:63], v[112:113]
	v_pk_mul_f32 v[122:123], v[70:71], v[84:85] op_sel_hi:[0,1]
	ds_read_b128 v[22:25], v94 offset:19232
	v_pk_fma_f32 v[110:111], v[120:121], v[48:49], v[110:111]
	v_pk_fma_f32 v[112:113], v[120:121], v[64:65], v[112:113]
	v_pk_mul_f32 v[124:125], v[70:71], v[86:87] op_sel_hi:[0,1]
	ds_read_b128 v[18:21], v94 offset:19248
	v_pk_fma_f32 v[110:111], v[122:123], v[42:43], v[110:111]
	v_pk_fma_f32 v[112:113], v[122:123], v[58:59], v[112:113]
	v_pk_mul_f32 v[126:127], v[70:71], v[88:89] op_sel_hi:[0,1]
	ds_read_b128 v[2:5], v94 offset:19456
	v_pk_fma_f32 v[110:111], v[124:125], v[44:45], v[110:111]
	v_pk_fma_f32 v[112:113], v[124:125], v[60:61], v[112:113]
	v_pk_mul_f32 v[128:129], v[70:71], v[90:91] op_sel_hi:[0,1]
	ds_read_b128 v[6:9], v94 offset:19472
	v_pk_fma_f32 v[110:111], v[126:127], v[38:39], v[110:111]
	v_pk_fma_f32 v[112:113], v[126:127], v[54:55], v[112:113]
	ds_read_b128 v[14:17], v94 offset:19488
	v_pk_fma_f32 v[110:111], v[128:129], v[40:41], v[110:111]
	v_pk_fma_f32 v[112:113], v[128:129], v[56:57], v[112:113]
	ds_read_b128 v[10:13], v94 offset:19504
	v_add_f32_e32 v134, v110, v111
	v_add_f32_e32 v135, v112, v113
	ds_read_b32 v73, v95 offset:19712
	v_add_f32_dpp v134, v134, v134 quad_perm:[1,0,3,2] row_mask:0xf bank_mask:0xf bound_ctrl:1
	v_add_f32_dpp v135, v135, v135 quad_perm:[1,0,3,2] row_mask:0xf bank_mask:0xf bound_ctrl:1
	ds_read_b96 v[34:36], v1 offset:19968
	v_add_f32_dpp v134, v134, v134 quad_perm:[2,3,0,1] row_mask:0xf bank_mask:0xf bound_ctrl:1
	v_add_f32_dpp v135, v135, v135 quad_perm:[2,3,0,1] row_mask:0xf bank_mask:0xf bound_ctrl:1
	v_sub_f32_e32 v134, v0, v134
	v_mul_f32_e32 v134, v71, v134
	v_fma_f32 v135, v72, v134, v135
	v_cvt_pk_bf16_f32 v133, v135, v135
	v_pk_fma_f32 v[74:75], v[50:51], v[134:135], v[114:115] op_sel_hi:[1,0,1]
	v_pk_fma_f32 v[78:79], v[52:53], v[134:135], v[116:117] op_sel_hi:[1,0,1]
	global_store_short v151, v133, s[100:101]
	v_pk_fma_f32 v[80:81], v[46:47], v[134:135], v[118:119] op_sel_hi:[1,0,1]
	v_pk_fma_f32 v[82:83], v[48:49], v[134:135], v[120:121] op_sel_hi:[1,0,1]
	v_pk_fma_f32 v[84:85], v[42:43], v[134:135], v[122:123] op_sel_hi:[1,0,1]
	v_pk_fma_f32 v[86:87], v[44:45], v[134:135], v[124:125] op_sel_hi:[1,0,1]
	v_pk_fma_f32 v[88:89], v[38:39], v[134:135], v[126:127] op_sel_hi:[1,0,1]
	v_pk_fma_f32 v[90:91], v[40:41], v[134:135], v[128:129] op_sel_hi:[1,0,1]
	s_waitcnt lgkmcnt(0)
	v_pk_mul_f32 v[114:115], v[34:35], v[74:75] op_sel_hi:[0,1]
	v_pk_mul_f32 v[116:117], v[34:35], v[78:79] op_sel_hi:[0,1]
	v_pk_fma_f32 v[106:107], v[114:115], v[2:3], 0 op_sel_hi:[1,1,0]
	v_pk_fma_f32 v[108:109], v[114:115], v[30:31], 0 op_sel_hi:[1,1,0]
	v_pk_mul_f32 v[118:119], v[34:35], v[80:81] op_sel_hi:[0,1]
	ds_read_b128 v[66:69], v94 offset:20000
	v_pk_fma_f32 v[106:107], v[116:117], v[4:5], v[106:107]
	v_pk_fma_f32 v[108:109], v[116:117], v[32:33], v[108:109]
	v_pk_mul_f32 v[120:121], v[34:35], v[82:83] op_sel_hi:[0,1]
	ds_read_b128 v[62:65], v94 offset:20016
	v_pk_fma_f32 v[106:107], v[118:119], v[6:7], v[106:107]
	v_pk_fma_f32 v[108:109], v[118:119], v[26:27], v[108:109]
	v_pk_mul_f32 v[122:123], v[34:35], v[84:85] op_sel_hi:[0,1]
	ds_read_b128 v[58:61], v94 offset:20032
	v_pk_fma_f32 v[106:107], v[120:121], v[8:9], v[106:107]
	v_pk_fma_f32 v[108:109], v[120:121], v[28:29], v[108:109]
	v_pk_mul_f32 v[124:125], v[34:35], v[86:87] op_sel_hi:[0,1]
	ds_read_b128 v[54:57], v94 offset:20048
	v_pk_fma_f32 v[106:107], v[122:123], v[14:15], v[106:107]
	v_pk_fma_f32 v[108:109], v[122:123], v[22:23], v[108:109]
	v_pk_mul_f32 v[126:127], v[34:35], v[88:89] op_sel_hi:[0,1]
	ds_read_b128 v[50:53], v94 offset:20256
	v_pk_fma_f32 v[106:107], v[124:125], v[16:17], v[106:107]
	v_pk_fma_f32 v[108:109], v[124:125], v[24:25], v[108:109]
	v_pk_mul_f32 v[128:129], v[34:35], v[90:91] op_sel_hi:[0,1]
	ds_read_b128 v[46:49], v94 offset:20272
	v_pk_fma_f32 v[106:107], v[126:127], v[10:11], v[106:107]
	v_pk_fma_f32 v[108:109], v[126:127], v[18:19], v[108:109]
	ds_read_b128 v[42:45], v94 offset:20288
	v_pk_fma_f32 v[106:107], v[128:129], v[12:13], v[106:107]
	v_pk_fma_f32 v[108:109], v[128:129], v[20:21], v[108:109]
	ds_read_b128 v[38:41], v94 offset:20304
	v_add_f32_e32 v130, v106, v107
	v_add_f32_e32 v131, v108, v109
	ds_read_b32 v0, v95 offset:20512
	v_add_f32_dpp v130, v130, v130 quad_perm:[1,0,3,2] row_mask:0xf bank_mask:0xf bound_ctrl:1
	v_add_f32_dpp v131, v131, v131 quad_perm:[1,0,3,2] row_mask:0xf bank_mask:0xf bound_ctrl:1
	ds_read_b96 v[70:72], v1 offset:20768
	v_add_f32_dpp v130, v130, v130 quad_perm:[2,3,0,1] row_mask:0xf bank_mask:0xf bound_ctrl:1
	v_add_f32_dpp v131, v131, v131 quad_perm:[2,3,0,1] row_mask:0xf bank_mask:0xf bound_ctrl:1
	v_sub_f32_e32 v130, v73, v130
	v_mul_f32_e32 v130, v35, v130
	v_fma_f32 v131, v36, v130, v131
	v_cvt_pk_bf16_f32 v132, v131, v131
	v_pk_fma_f32 v[74:75], v[2:3], v[130:131], v[114:115] op_sel_hi:[1,0,1]
	v_pk_fma_f32 v[78:79], v[4:5], v[130:131], v[116:117] op_sel_hi:[1,0,1]
	global_store_short v152, v132, s[100:101]
	v_pk_fma_f32 v[80:81], v[6:7], v[130:131], v[118:119] op_sel_hi:[1,0,1]
	v_pk_fma_f32 v[82:83], v[8:9], v[130:131], v[120:121] op_sel_hi:[1,0,1]
	v_pk_fma_f32 v[84:85], v[14:15], v[130:131], v[122:123] op_sel_hi:[1,0,1]
	v_pk_fma_f32 v[86:87], v[16:17], v[130:131], v[124:125] op_sel_hi:[1,0,1]
	v_pk_fma_f32 v[88:89], v[10:11], v[130:131], v[126:127] op_sel_hi:[1,0,1]
	v_pk_fma_f32 v[90:91], v[12:13], v[130:131], v[128:129] op_sel_hi:[1,0,1]
	s_waitcnt lgkmcnt(0)
	v_pk_mul_f32 v[114:115], v[70:71], v[74:75] op_sel_hi:[0,1]
	v_pk_mul_f32 v[116:117], v[70:71], v[78:79] op_sel_hi:[0,1]
	v_pk_fma_f32 v[110:111], v[114:115], v[50:51], 0 op_sel_hi:[1,1,0]
	v_pk_fma_f32 v[112:113], v[114:115], v[66:67], 0 op_sel_hi:[1,1,0]
	v_pk_mul_f32 v[118:119], v[70:71], v[80:81] op_sel_hi:[0,1]
	ds_read_b128 v[30:33], v94 offset:20800
	v_pk_fma_f32 v[110:111], v[116:117], v[52:53], v[110:111]
	v_pk_fma_f32 v[112:113], v[116:117], v[68:69], v[112:113]
	v_pk_mul_f32 v[120:121], v[70:71], v[82:83] op_sel_hi:[0,1]
	ds_read_b128 v[26:29], v94 offset:20816
	v_pk_fma_f32 v[110:111], v[118:119], v[46:47], v[110:111]
	v_pk_fma_f32 v[112:113], v[118:119], v[62:63], v[112:113]
	v_pk_mul_f32 v[122:123], v[70:71], v[84:85] op_sel_hi:[0,1]
	ds_read_b128 v[22:25], v94 offset:20832
	v_pk_fma_f32 v[110:111], v[120:121], v[48:49], v[110:111]
	v_pk_fma_f32 v[112:113], v[120:121], v[64:65], v[112:113]
	v_pk_mul_f32 v[124:125], v[70:71], v[86:87] op_sel_hi:[0,1]
	ds_read_b128 v[18:21], v94 offset:20848
	v_pk_fma_f32 v[110:111], v[122:123], v[42:43], v[110:111]
	v_pk_fma_f32 v[112:113], v[122:123], v[58:59], v[112:113]
	v_pk_mul_f32 v[126:127], v[70:71], v[88:89] op_sel_hi:[0,1]
	ds_read_b128 v[2:5], v94 offset:21056
	v_pk_fma_f32 v[110:111], v[124:125], v[44:45], v[110:111]
	v_pk_fma_f32 v[112:113], v[124:125], v[60:61], v[112:113]
	v_pk_mul_f32 v[128:129], v[70:71], v[90:91] op_sel_hi:[0,1]
	ds_read_b128 v[6:9], v94 offset:21072
	v_pk_fma_f32 v[110:111], v[126:127], v[38:39], v[110:111]
	v_pk_fma_f32 v[112:113], v[126:127], v[54:55], v[112:113]
	ds_read_b128 v[14:17], v94 offset:21088
	v_pk_fma_f32 v[110:111], v[128:129], v[40:41], v[110:111]
	v_pk_fma_f32 v[112:113], v[128:129], v[56:57], v[112:113]
	ds_read_b128 v[10:13], v94 offset:21104
	v_add_f32_e32 v134, v110, v111
	v_add_f32_e32 v135, v112, v113
	ds_read_b32 v73, v95 offset:21312
	v_add_f32_dpp v134, v134, v134 quad_perm:[1,0,3,2] row_mask:0xf bank_mask:0xf bound_ctrl:1
	v_add_f32_dpp v135, v135, v135 quad_perm:[1,0,3,2] row_mask:0xf bank_mask:0xf bound_ctrl:1
	ds_read_b96 v[34:36], v1 offset:21568
	v_add_f32_dpp v134, v134, v134 quad_perm:[2,3,0,1] row_mask:0xf bank_mask:0xf bound_ctrl:1
	v_add_f32_dpp v135, v135, v135 quad_perm:[2,3,0,1] row_mask:0xf bank_mask:0xf bound_ctrl:1
	v_sub_f32_e32 v134, v0, v134
	v_mul_f32_e32 v134, v71, v134
	v_fma_f32 v135, v72, v134, v135
	v_cvt_pk_bf16_f32 v133, v135, v135
	v_pk_fma_f32 v[74:75], v[50:51], v[134:135], v[114:115] op_sel_hi:[1,0,1]
	v_pk_fma_f32 v[78:79], v[52:53], v[134:135], v[116:117] op_sel_hi:[1,0,1]
	global_store_short v153, v133, s[100:101]
	v_pk_fma_f32 v[80:81], v[46:47], v[134:135], v[118:119] op_sel_hi:[1,0,1]
	v_pk_fma_f32 v[82:83], v[48:49], v[134:135], v[120:121] op_sel_hi:[1,0,1]
	v_pk_fma_f32 v[84:85], v[42:43], v[134:135], v[122:123] op_sel_hi:[1,0,1]
	v_pk_fma_f32 v[86:87], v[44:45], v[134:135], v[124:125] op_sel_hi:[1,0,1]
	v_pk_fma_f32 v[88:89], v[38:39], v[134:135], v[126:127] op_sel_hi:[1,0,1]
	v_pk_fma_f32 v[90:91], v[40:41], v[134:135], v[128:129] op_sel_hi:[1,0,1]
	s_waitcnt lgkmcnt(0)
	v_pk_mul_f32 v[114:115], v[34:35], v[74:75] op_sel_hi:[0,1]
	v_pk_mul_f32 v[116:117], v[34:35], v[78:79] op_sel_hi:[0,1]
	v_pk_fma_f32 v[106:107], v[114:115], v[2:3], 0 op_sel_hi:[1,1,0]
	v_pk_fma_f32 v[108:109], v[114:115], v[30:31], 0 op_sel_hi:[1,1,0]
	v_pk_mul_f32 v[118:119], v[34:35], v[80:81] op_sel_hi:[0,1]
	ds_read_b128 v[66:69], v94 offset:21600
	v_pk_fma_f32 v[106:107], v[116:117], v[4:5], v[106:107]
	v_pk_fma_f32 v[108:109], v[116:117], v[32:33], v[108:109]
	v_pk_mul_f32 v[120:121], v[34:35], v[82:83] op_sel_hi:[0,1]
	ds_read_b128 v[62:65], v94 offset:21616
	v_pk_fma_f32 v[106:107], v[118:119], v[6:7], v[106:107]
	v_pk_fma_f32 v[108:109], v[118:119], v[26:27], v[108:109]
	v_pk_mul_f32 v[122:123], v[34:35], v[84:85] op_sel_hi:[0,1]
	ds_read_b128 v[58:61], v94 offset:21632
	v_pk_fma_f32 v[106:107], v[120:121], v[8:9], v[106:107]
	v_pk_fma_f32 v[108:109], v[120:121], v[28:29], v[108:109]
	v_pk_mul_f32 v[124:125], v[34:35], v[86:87] op_sel_hi:[0,1]
	ds_read_b128 v[54:57], v94 offset:21648
	v_pk_fma_f32 v[106:107], v[122:123], v[14:15], v[106:107]
	v_pk_fma_f32 v[108:109], v[122:123], v[22:23], v[108:109]
	v_pk_mul_f32 v[126:127], v[34:35], v[88:89] op_sel_hi:[0,1]
	ds_read_b128 v[50:53], v94 offset:21856
	v_pk_fma_f32 v[106:107], v[124:125], v[16:17], v[106:107]
	v_pk_fma_f32 v[108:109], v[124:125], v[24:25], v[108:109]
	v_pk_mul_f32 v[128:129], v[34:35], v[90:91] op_sel_hi:[0,1]
	ds_read_b128 v[46:49], v94 offset:21872
	v_pk_fma_f32 v[106:107], v[126:127], v[10:11], v[106:107]
	v_pk_fma_f32 v[108:109], v[126:127], v[18:19], v[108:109]
	ds_read_b128 v[42:45], v94 offset:21888
	v_pk_fma_f32 v[106:107], v[128:129], v[12:13], v[106:107]
	v_pk_fma_f32 v[108:109], v[128:129], v[20:21], v[108:109]
	ds_read_b128 v[38:41], v94 offset:21904
	v_add_f32_e32 v130, v106, v107
	v_add_f32_e32 v131, v108, v109
	ds_read_b32 v0, v95 offset:22112
	v_add_f32_dpp v130, v130, v130 quad_perm:[1,0,3,2] row_mask:0xf bank_mask:0xf bound_ctrl:1
	v_add_f32_dpp v131, v131, v131 quad_perm:[1,0,3,2] row_mask:0xf bank_mask:0xf bound_ctrl:1
	ds_read_b96 v[70:72], v1 offset:22368
	v_add_f32_dpp v130, v130, v130 quad_perm:[2,3,0,1] row_mask:0xf bank_mask:0xf bound_ctrl:1
	v_add_f32_dpp v131, v131, v131 quad_perm:[2,3,0,1] row_mask:0xf bank_mask:0xf bound_ctrl:1
	v_sub_f32_e32 v130, v73, v130
	v_mul_f32_e32 v130, v35, v130
	v_fma_f32 v131, v36, v130, v131
	v_cvt_pk_bf16_f32 v132, v131, v131
	v_pk_fma_f32 v[74:75], v[2:3], v[130:131], v[114:115] op_sel_hi:[1,0,1]
	v_pk_fma_f32 v[78:79], v[4:5], v[130:131], v[116:117] op_sel_hi:[1,0,1]
	global_store_short v154, v132, s[100:101]
	v_pk_fma_f32 v[80:81], v[6:7], v[130:131], v[118:119] op_sel_hi:[1,0,1]
	v_pk_fma_f32 v[82:83], v[8:9], v[130:131], v[120:121] op_sel_hi:[1,0,1]
	v_pk_fma_f32 v[84:85], v[14:15], v[130:131], v[122:123] op_sel_hi:[1,0,1]
	v_pk_fma_f32 v[86:87], v[16:17], v[130:131], v[124:125] op_sel_hi:[1,0,1]
	v_pk_fma_f32 v[88:89], v[10:11], v[130:131], v[126:127] op_sel_hi:[1,0,1]
	v_pk_fma_f32 v[90:91], v[12:13], v[130:131], v[128:129] op_sel_hi:[1,0,1]
	s_waitcnt lgkmcnt(0)
	v_pk_mul_f32 v[114:115], v[70:71], v[74:75] op_sel_hi:[0,1]
	v_pk_mul_f32 v[116:117], v[70:71], v[78:79] op_sel_hi:[0,1]
	v_pk_fma_f32 v[110:111], v[114:115], v[50:51], 0 op_sel_hi:[1,1,0]
	v_pk_fma_f32 v[112:113], v[114:115], v[66:67], 0 op_sel_hi:[1,1,0]
	v_pk_mul_f32 v[118:119], v[70:71], v[80:81] op_sel_hi:[0,1]
	ds_read_b128 v[30:33], v94 offset:22400
	v_pk_fma_f32 v[110:111], v[116:117], v[52:53], v[110:111]
	v_pk_fma_f32 v[112:113], v[116:117], v[68:69], v[112:113]
	v_pk_mul_f32 v[120:121], v[70:71], v[82:83] op_sel_hi:[0,1]
	ds_read_b128 v[26:29], v94 offset:22416
	v_pk_fma_f32 v[110:111], v[118:119], v[46:47], v[110:111]
	v_pk_fma_f32 v[112:113], v[118:119], v[62:63], v[112:113]
	v_pk_mul_f32 v[122:123], v[70:71], v[84:85] op_sel_hi:[0,1]
	ds_read_b128 v[22:25], v94 offset:22432
	v_pk_fma_f32 v[110:111], v[120:121], v[48:49], v[110:111]
	v_pk_fma_f32 v[112:113], v[120:121], v[64:65], v[112:113]
	v_pk_mul_f32 v[124:125], v[70:71], v[86:87] op_sel_hi:[0,1]
	ds_read_b128 v[18:21], v94 offset:22448
	v_pk_fma_f32 v[110:111], v[122:123], v[42:43], v[110:111]
	v_pk_fma_f32 v[112:113], v[122:123], v[58:59], v[112:113]
	v_pk_mul_f32 v[126:127], v[70:71], v[88:89] op_sel_hi:[0,1]
	ds_read_b128 v[2:5], v94 offset:22656
	v_pk_fma_f32 v[110:111], v[124:125], v[44:45], v[110:111]
	v_pk_fma_f32 v[112:113], v[124:125], v[60:61], v[112:113]
	v_pk_mul_f32 v[128:129], v[70:71], v[90:91] op_sel_hi:[0,1]
	ds_read_b128 v[6:9], v94 offset:22672
	v_pk_fma_f32 v[110:111], v[126:127], v[38:39], v[110:111]
	v_pk_fma_f32 v[112:113], v[126:127], v[54:55], v[112:113]
	ds_read_b128 v[14:17], v94 offset:22688
	v_pk_fma_f32 v[110:111], v[128:129], v[40:41], v[110:111]
	v_pk_fma_f32 v[112:113], v[128:129], v[56:57], v[112:113]
	ds_read_b128 v[10:13], v94 offset:22704
	v_add_f32_e32 v134, v110, v111
	v_add_f32_e32 v135, v112, v113
	ds_read_b32 v73, v95 offset:22912
	v_add_f32_dpp v134, v134, v134 quad_perm:[1,0,3,2] row_mask:0xf bank_mask:0xf bound_ctrl:1
	v_add_f32_dpp v135, v135, v135 quad_perm:[1,0,3,2] row_mask:0xf bank_mask:0xf bound_ctrl:1
	ds_read_b96 v[34:36], v1 offset:23168
	v_add_f32_dpp v134, v134, v134 quad_perm:[2,3,0,1] row_mask:0xf bank_mask:0xf bound_ctrl:1
	v_add_f32_dpp v135, v135, v135 quad_perm:[2,3,0,1] row_mask:0xf bank_mask:0xf bound_ctrl:1
	v_sub_f32_e32 v134, v0, v134
	v_mul_f32_e32 v134, v71, v134
	v_fma_f32 v135, v72, v134, v135
	v_cvt_pk_bf16_f32 v133, v135, v135
	v_pk_fma_f32 v[74:75], v[50:51], v[134:135], v[114:115] op_sel_hi:[1,0,1]
	v_pk_fma_f32 v[78:79], v[52:53], v[134:135], v[116:117] op_sel_hi:[1,0,1]
	global_store_short v155, v133, s[100:101]
	v_pk_fma_f32 v[80:81], v[46:47], v[134:135], v[118:119] op_sel_hi:[1,0,1]
	v_pk_fma_f32 v[82:83], v[48:49], v[134:135], v[120:121] op_sel_hi:[1,0,1]
	v_pk_fma_f32 v[84:85], v[42:43], v[134:135], v[122:123] op_sel_hi:[1,0,1]
	v_pk_fma_f32 v[86:87], v[44:45], v[134:135], v[124:125] op_sel_hi:[1,0,1]
	v_pk_fma_f32 v[88:89], v[38:39], v[134:135], v[126:127] op_sel_hi:[1,0,1]
	v_pk_fma_f32 v[90:91], v[40:41], v[134:135], v[128:129] op_sel_hi:[1,0,1]
	s_waitcnt lgkmcnt(0)
	v_pk_mul_f32 v[114:115], v[34:35], v[74:75] op_sel_hi:[0,1]
	v_pk_mul_f32 v[116:117], v[34:35], v[78:79] op_sel_hi:[0,1]
	v_pk_fma_f32 v[106:107], v[114:115], v[2:3], 0 op_sel_hi:[1,1,0]
	v_pk_fma_f32 v[108:109], v[114:115], v[30:31], 0 op_sel_hi:[1,1,0]
	v_pk_mul_f32 v[118:119], v[34:35], v[80:81] op_sel_hi:[0,1]
	ds_read_b128 v[66:69], v94 offset:23200
	v_pk_fma_f32 v[106:107], v[116:117], v[4:5], v[106:107]
	v_pk_fma_f32 v[108:109], v[116:117], v[32:33], v[108:109]
	v_pk_mul_f32 v[120:121], v[34:35], v[82:83] op_sel_hi:[0,1]
	ds_read_b128 v[62:65], v94 offset:23216
	v_pk_fma_f32 v[106:107], v[118:119], v[6:7], v[106:107]
	v_pk_fma_f32 v[108:109], v[118:119], v[26:27], v[108:109]
	v_pk_mul_f32 v[122:123], v[34:35], v[84:85] op_sel_hi:[0,1]
	ds_read_b128 v[58:61], v94 offset:23232
	v_pk_fma_f32 v[106:107], v[120:121], v[8:9], v[106:107]
	v_pk_fma_f32 v[108:109], v[120:121], v[28:29], v[108:109]
	v_pk_mul_f32 v[124:125], v[34:35], v[86:87] op_sel_hi:[0,1]
	ds_read_b128 v[54:57], v94 offset:23248
	v_pk_fma_f32 v[106:107], v[122:123], v[14:15], v[106:107]
	v_pk_fma_f32 v[108:109], v[122:123], v[22:23], v[108:109]
	v_pk_mul_f32 v[126:127], v[34:35], v[88:89] op_sel_hi:[0,1]
	ds_read_b128 v[50:53], v94 offset:23456
	v_pk_fma_f32 v[106:107], v[124:125], v[16:17], v[106:107]
	v_pk_fma_f32 v[108:109], v[124:125], v[24:25], v[108:109]
	v_pk_mul_f32 v[128:129], v[34:35], v[90:91] op_sel_hi:[0,1]
	ds_read_b128 v[46:49], v94 offset:23472
	v_pk_fma_f32 v[106:107], v[126:127], v[10:11], v[106:107]
	v_pk_fma_f32 v[108:109], v[126:127], v[18:19], v[108:109]
	ds_read_b128 v[42:45], v94 offset:23488
	v_pk_fma_f32 v[106:107], v[128:129], v[12:13], v[106:107]
	v_pk_fma_f32 v[108:109], v[128:129], v[20:21], v[108:109]
	ds_read_b128 v[38:41], v94 offset:23504
	v_add_f32_e32 v130, v106, v107
	v_add_f32_e32 v131, v108, v109
	ds_read_b32 v0, v95 offset:23712
	v_add_f32_dpp v130, v130, v130 quad_perm:[1,0,3,2] row_mask:0xf bank_mask:0xf bound_ctrl:1
	v_add_f32_dpp v131, v131, v131 quad_perm:[1,0,3,2] row_mask:0xf bank_mask:0xf bound_ctrl:1
	ds_read_b96 v[70:72], v1 offset:23968
	v_add_f32_dpp v130, v130, v130 quad_perm:[2,3,0,1] row_mask:0xf bank_mask:0xf bound_ctrl:1
	v_add_f32_dpp v131, v131, v131 quad_perm:[2,3,0,1] row_mask:0xf bank_mask:0xf bound_ctrl:1
	v_sub_f32_e32 v130, v73, v130
	v_mul_f32_e32 v130, v35, v130
	v_fma_f32 v131, v36, v130, v131
	v_cvt_pk_bf16_f32 v132, v131, v131
	v_pk_fma_f32 v[74:75], v[2:3], v[130:131], v[114:115] op_sel_hi:[1,0,1]
	v_pk_fma_f32 v[78:79], v[4:5], v[130:131], v[116:117] op_sel_hi:[1,0,1]
	global_store_short v156, v132, s[100:101]
	v_pk_fma_f32 v[80:81], v[6:7], v[130:131], v[118:119] op_sel_hi:[1,0,1]
	v_pk_fma_f32 v[82:83], v[8:9], v[130:131], v[120:121] op_sel_hi:[1,0,1]
	v_pk_fma_f32 v[84:85], v[14:15], v[130:131], v[122:123] op_sel_hi:[1,0,1]
	v_pk_fma_f32 v[86:87], v[16:17], v[130:131], v[124:125] op_sel_hi:[1,0,1]
	v_pk_fma_f32 v[88:89], v[10:11], v[130:131], v[126:127] op_sel_hi:[1,0,1]
	v_pk_fma_f32 v[90:91], v[12:13], v[130:131], v[128:129] op_sel_hi:[1,0,1]
	s_waitcnt lgkmcnt(0)
	v_pk_mul_f32 v[114:115], v[70:71], v[74:75] op_sel_hi:[0,1]
	v_pk_mul_f32 v[116:117], v[70:71], v[78:79] op_sel_hi:[0,1]
	v_pk_fma_f32 v[110:111], v[114:115], v[50:51], 0 op_sel_hi:[1,1,0]
	v_pk_fma_f32 v[112:113], v[114:115], v[66:67], 0 op_sel_hi:[1,1,0]
	v_pk_mul_f32 v[118:119], v[70:71], v[80:81] op_sel_hi:[0,1]
	ds_read_b128 v[30:33], v94 offset:24000
	v_pk_fma_f32 v[110:111], v[116:117], v[52:53], v[110:111]
	v_pk_fma_f32 v[112:113], v[116:117], v[68:69], v[112:113]
	v_pk_mul_f32 v[120:121], v[70:71], v[82:83] op_sel_hi:[0,1]
	ds_read_b128 v[26:29], v94 offset:24016
	v_pk_fma_f32 v[110:111], v[118:119], v[46:47], v[110:111]
	v_pk_fma_f32 v[112:113], v[118:119], v[62:63], v[112:113]
	v_pk_mul_f32 v[122:123], v[70:71], v[84:85] op_sel_hi:[0,1]
	ds_read_b128 v[22:25], v94 offset:24032
	v_pk_fma_f32 v[110:111], v[120:121], v[48:49], v[110:111]
	v_pk_fma_f32 v[112:113], v[120:121], v[64:65], v[112:113]
	v_pk_mul_f32 v[124:125], v[70:71], v[86:87] op_sel_hi:[0,1]
	ds_read_b128 v[18:21], v94 offset:24048
	v_pk_fma_f32 v[110:111], v[122:123], v[42:43], v[110:111]
	v_pk_fma_f32 v[112:113], v[122:123], v[58:59], v[112:113]
	v_pk_mul_f32 v[126:127], v[70:71], v[88:89] op_sel_hi:[0,1]
	ds_read_b128 v[2:5], v94 offset:24256
	v_pk_fma_f32 v[110:111], v[124:125], v[44:45], v[110:111]
	v_pk_fma_f32 v[112:113], v[124:125], v[60:61], v[112:113]
	v_pk_mul_f32 v[128:129], v[70:71], v[90:91] op_sel_hi:[0,1]
	ds_read_b128 v[6:9], v94 offset:24272
	v_pk_fma_f32 v[110:111], v[126:127], v[38:39], v[110:111]
	v_pk_fma_f32 v[112:113], v[126:127], v[54:55], v[112:113]
	ds_read_b128 v[14:17], v94 offset:24288
	v_pk_fma_f32 v[110:111], v[128:129], v[40:41], v[110:111]
	v_pk_fma_f32 v[112:113], v[128:129], v[56:57], v[112:113]
	ds_read_b128 v[10:13], v94 offset:24304
	v_add_f32_e32 v134, v110, v111
	v_add_f32_e32 v135, v112, v113
	ds_read_b32 v73, v95 offset:24512
	v_add_f32_dpp v134, v134, v134 quad_perm:[1,0,3,2] row_mask:0xf bank_mask:0xf bound_ctrl:1
	v_add_f32_dpp v135, v135, v135 quad_perm:[1,0,3,2] row_mask:0xf bank_mask:0xf bound_ctrl:1
	ds_read_b96 v[34:36], v1 offset:24768
	v_add_f32_dpp v134, v134, v134 quad_perm:[2,3,0,1] row_mask:0xf bank_mask:0xf bound_ctrl:1
	v_add_f32_dpp v135, v135, v135 quad_perm:[2,3,0,1] row_mask:0xf bank_mask:0xf bound_ctrl:1
	v_sub_f32_e32 v134, v0, v134
	v_mul_f32_e32 v134, v71, v134
	v_fma_f32 v135, v72, v134, v135
	v_cvt_pk_bf16_f32 v133, v135, v135
	v_pk_fma_f32 v[74:75], v[50:51], v[134:135], v[114:115] op_sel_hi:[1,0,1]
	v_pk_fma_f32 v[78:79], v[52:53], v[134:135], v[116:117] op_sel_hi:[1,0,1]
	global_store_short v157, v133, s[100:101]
	v_pk_fma_f32 v[80:81], v[46:47], v[134:135], v[118:119] op_sel_hi:[1,0,1]
	v_pk_fma_f32 v[82:83], v[48:49], v[134:135], v[120:121] op_sel_hi:[1,0,1]
	v_pk_fma_f32 v[84:85], v[42:43], v[134:135], v[122:123] op_sel_hi:[1,0,1]
	v_pk_fma_f32 v[86:87], v[44:45], v[134:135], v[124:125] op_sel_hi:[1,0,1]
	v_pk_fma_f32 v[88:89], v[38:39], v[134:135], v[126:127] op_sel_hi:[1,0,1]
	v_pk_fma_f32 v[90:91], v[40:41], v[134:135], v[128:129] op_sel_hi:[1,0,1]
	s_waitcnt lgkmcnt(0)
	v_pk_mul_f32 v[114:115], v[34:35], v[74:75] op_sel_hi:[0,1]
	v_pk_mul_f32 v[116:117], v[34:35], v[78:79] op_sel_hi:[0,1]
	v_pk_fma_f32 v[106:107], v[114:115], v[2:3], 0 op_sel_hi:[1,1,0]
	v_pk_fma_f32 v[108:109], v[114:115], v[30:31], 0 op_sel_hi:[1,1,0]
	v_pk_mul_f32 v[118:119], v[34:35], v[80:81] op_sel_hi:[0,1]
	ds_read_b128 v[66:69], v94 offset:24800
	v_pk_fma_f32 v[106:107], v[116:117], v[4:5], v[106:107]
	v_pk_fma_f32 v[108:109], v[116:117], v[32:33], v[108:109]
	v_pk_mul_f32 v[120:121], v[34:35], v[82:83] op_sel_hi:[0,1]
	ds_read_b128 v[62:65], v94 offset:24816
	v_pk_fma_f32 v[106:107], v[118:119], v[6:7], v[106:107]
	v_pk_fma_f32 v[108:109], v[118:119], v[26:27], v[108:109]
	v_pk_mul_f32 v[122:123], v[34:35], v[84:85] op_sel_hi:[0,1]
	ds_read_b128 v[58:61], v94 offset:24832
	v_pk_fma_f32 v[106:107], v[120:121], v[8:9], v[106:107]
	v_pk_fma_f32 v[108:109], v[120:121], v[28:29], v[108:109]
	v_pk_mul_f32 v[124:125], v[34:35], v[86:87] op_sel_hi:[0,1]
	ds_read_b128 v[54:57], v94 offset:24848
	v_pk_fma_f32 v[106:107], v[122:123], v[14:15], v[106:107]
	v_pk_fma_f32 v[108:109], v[122:123], v[22:23], v[108:109]
	v_pk_mul_f32 v[126:127], v[34:35], v[88:89] op_sel_hi:[0,1]
	ds_read_b128 v[50:53], v94 offset:25056
	v_pk_fma_f32 v[106:107], v[124:125], v[16:17], v[106:107]
	v_pk_fma_f32 v[108:109], v[124:125], v[24:25], v[108:109]
	v_pk_mul_f32 v[128:129], v[34:35], v[90:91] op_sel_hi:[0,1]
	ds_read_b128 v[46:49], v94 offset:25072
	v_pk_fma_f32 v[106:107], v[126:127], v[10:11], v[106:107]
	v_pk_fma_f32 v[108:109], v[126:127], v[18:19], v[108:109]
	ds_read_b128 v[42:45], v94 offset:25088
	v_pk_fma_f32 v[106:107], v[128:129], v[12:13], v[106:107]
	v_pk_fma_f32 v[108:109], v[128:129], v[20:21], v[108:109]
	ds_read_b128 v[38:41], v94 offset:25104
	v_add_f32_e32 v130, v106, v107
	v_add_f32_e32 v131, v108, v109
	ds_read_b32 v0, v95 offset:25312
	v_add_f32_dpp v130, v130, v130 quad_perm:[1,0,3,2] row_mask:0xf bank_mask:0xf bound_ctrl:1
	v_add_f32_dpp v131, v131, v131 quad_perm:[1,0,3,2] row_mask:0xf bank_mask:0xf bound_ctrl:1
	ds_read_b96 v[70:72], v1 offset:25568
	v_add_f32_dpp v130, v130, v130 quad_perm:[2,3,0,1] row_mask:0xf bank_mask:0xf bound_ctrl:1
	v_add_f32_dpp v131, v131, v131 quad_perm:[2,3,0,1] row_mask:0xf bank_mask:0xf bound_ctrl:1
	v_sub_f32_e32 v130, v73, v130
	v_mul_f32_e32 v130, v35, v130
	v_fma_f32 v131, v36, v130, v131
	v_cvt_pk_bf16_f32 v132, v131, v131
	v_pk_fma_f32 v[74:75], v[2:3], v[130:131], v[114:115] op_sel_hi:[1,0,1]
	v_pk_fma_f32 v[78:79], v[4:5], v[130:131], v[116:117] op_sel_hi:[1,0,1]
	global_store_short v158, v132, s[100:101]
	v_pk_fma_f32 v[80:81], v[6:7], v[130:131], v[118:119] op_sel_hi:[1,0,1]
	v_pk_fma_f32 v[82:83], v[8:9], v[130:131], v[120:121] op_sel_hi:[1,0,1]
	v_pk_fma_f32 v[84:85], v[14:15], v[130:131], v[122:123] op_sel_hi:[1,0,1]
	v_pk_fma_f32 v[86:87], v[16:17], v[130:131], v[124:125] op_sel_hi:[1,0,1]
	v_pk_fma_f32 v[88:89], v[10:11], v[130:131], v[126:127] op_sel_hi:[1,0,1]
	v_pk_fma_f32 v[90:91], v[12:13], v[130:131], v[128:129] op_sel_hi:[1,0,1]
	s_waitcnt lgkmcnt(0)
	v_pk_mul_f32 v[114:115], v[70:71], v[74:75] op_sel_hi:[0,1]
	v_pk_mul_f32 v[116:117], v[70:71], v[78:79] op_sel_hi:[0,1]
	v_pk_fma_f32 v[110:111], v[114:115], v[50:51], 0 op_sel_hi:[1,1,0]
	v_pk_fma_f32 v[112:113], v[114:115], v[66:67], 0 op_sel_hi:[1,1,0]
	v_pk_mul_f32 v[118:119], v[70:71], v[80:81] op_sel_hi:[0,1]
	v_pk_fma_f32 v[110:111], v[116:117], v[52:53], v[110:111]
	v_pk_fma_f32 v[112:113], v[116:117], v[68:69], v[112:113]
	v_pk_mul_f32 v[120:121], v[70:71], v[82:83] op_sel_hi:[0,1]
	v_pk_fma_f32 v[110:111], v[118:119], v[46:47], v[110:111]
	v_pk_fma_f32 v[112:113], v[118:119], v[62:63], v[112:113]
	v_pk_mul_f32 v[122:123], v[70:71], v[84:85] op_sel_hi:[0,1]
	v_pk_fma_f32 v[110:111], v[120:121], v[48:49], v[110:111]
	v_pk_fma_f32 v[112:113], v[120:121], v[64:65], v[112:113]
	v_pk_mul_f32 v[124:125], v[70:71], v[86:87] op_sel_hi:[0,1]
	v_pk_fma_f32 v[110:111], v[122:123], v[42:43], v[110:111]
	v_pk_fma_f32 v[112:113], v[122:123], v[58:59], v[112:113]
	v_pk_mul_f32 v[126:127], v[70:71], v[88:89] op_sel_hi:[0,1]
	v_pk_fma_f32 v[110:111], v[124:125], v[44:45], v[110:111]
	v_pk_fma_f32 v[112:113], v[124:125], v[60:61], v[112:113]
	v_pk_mul_f32 v[128:129], v[70:71], v[90:91] op_sel_hi:[0,1]
	v_pk_fma_f32 v[110:111], v[126:127], v[38:39], v[110:111]
	v_pk_fma_f32 v[112:113], v[126:127], v[54:55], v[112:113]
	v_pk_fma_f32 v[110:111], v[128:129], v[40:41], v[110:111]
	v_pk_fma_f32 v[112:113], v[128:129], v[56:57], v[112:113]
	v_add_f32_e32 v134, v110, v111
	v_add_f32_e32 v135, v112, v113
	s_nop 0
	v_add_f32_dpp v134, v134, v134 quad_perm:[1,0,3,2] row_mask:0xf bank_mask:0xf bound_ctrl:1
	v_add_f32_dpp v135, v135, v135 quad_perm:[1,0,3,2] row_mask:0xf bank_mask:0xf bound_ctrl:1
	s_nop 0
	v_add_f32_dpp v134, v134, v134 quad_perm:[2,3,0,1] row_mask:0xf bank_mask:0xf bound_ctrl:1
	v_add_f32_dpp v135, v135, v135 quad_perm:[2,3,0,1] row_mask:0xf bank_mask:0xf bound_ctrl:1
	v_sub_f32_e32 v134, v0, v134
	v_mul_f32_e32 v134, v71, v134
	v_fma_f32 v135, v72, v134, v135
	v_cvt_pk_bf16_f32 v133, v135, v135
	v_pk_fma_f32 v[74:75], v[50:51], v[134:135], v[114:115] op_sel_hi:[1,0,1]
	v_pk_fma_f32 v[78:79], v[52:53], v[134:135], v[116:117] op_sel_hi:[1,0,1]
	global_store_short v159, v133, s[100:101]
	v_pk_fma_f32 v[80:81], v[46:47], v[134:135], v[118:119] op_sel_hi:[1,0,1]
	v_pk_fma_f32 v[82:83], v[48:49], v[134:135], v[120:121] op_sel_hi:[1,0,1]
	v_pk_fma_f32 v[84:85], v[42:43], v[134:135], v[122:123] op_sel_hi:[1,0,1]
	v_pk_fma_f32 v[86:87], v[44:45], v[134:135], v[124:125] op_sel_hi:[1,0,1]
	v_pk_fma_f32 v[88:89], v[38:39], v[134:135], v[126:127] op_sel_hi:[1,0,1]
	v_pk_fma_f32 v[90:91], v[40:41], v[134:135], v[128:129] op_sel_hi:[1,0,1]
	s_branch .LBB0_899
